# K-loop load segments made VALU-free: LDS-DMA uses SGPR-base saddr addressing, ds_read base addresses hoisted
# speedup vs baseline: 1.0030x; 1.0030x over previous
.LBB0_245:
	s_ashr_i32 s69, s68, 31
	s_lshl_b64 s[56:57], s[68:69], 20
	s_add_u32 s33, s14, s56
	s_addc_u32 s48, s15, s57
	s_ashr_i32 s75, s74, 31
	s_lshl_b64 s[56:57], s[74:75], 7
	s_add_u32 s84, s33, s56
	s_addc_u32 s85, s48, s57
	s_and_b64 s[76:77], s[90:91], exec
	s_cselect_b32 s69, s85, s1
	s_cselect_b32 s75, s84, s0
	s_ashr_i32 s73, s72, 31
	s_lshl_b64 s[76:77], s[72:73], 20
	s_add_u32 s33, s9, s76
	s_addc_u32 s48, s23, s77
	s_add_u32 s86, s33, s56
	s_addc_u32 s87, s48, s57
	s_and_b64 s[56:57], s[90:91], exec
	s_cselect_b32 s73, s87, s89
	s_cselect_b32 vcc_lo, s86, s88
	s_add_i32 vcc_hi, s55, -2
	s_add_u32 s0, s0, 0x80080
	s_addc_u32 s1, s1, 0
	s_add_u32 s56, s88, 0x100
	s_addc_u32 s57, s89, 0
	s_mov_b32 s88, 0
	v_mov_b64_e32 v[4:5], 0
	v_mov_b64_e32 v[6:7], 0
	v_mov_b64_e32 v[8:9], 0
	v_mov_b64_e32 v[10:11], 0
	v_mov_b64_e32 v[12:13], 0
	v_mov_b64_e32 v[14:15], 0
	v_mov_b64_e32 v[16:17], 0
	v_mov_b64_e32 v[18:19], 0
	v_mov_b64_e32 v[20:21], 0
	v_mov_b64_e32 v[22:23], 0
	v_mov_b64_e32 v[24:25], 0
	v_mov_b64_e32 v[26:27], 0
	v_mov_b64_e32 v[28:29], 0
	v_mov_b64_e32 v[30:31], 0
	v_mov_b64_e32 v[32:33], 0
	v_mov_b64_e32 v[34:35], 0
	v_mov_b64_e32 v[36:37], 0
	v_mov_b64_e32 v[38:39], 0
	v_mov_b64_e32 v[40:41], 0
	v_mov_b64_e32 v[42:43], 0
	v_mov_b64_e32 v[44:45], 0
	v_mov_b64_e32 v[46:47], 0
	v_mov_b64_e32 v[48:49], 0
	v_mov_b64_e32 v[50:51], 0
	v_mov_b64_e32 v[52:53], 0
	v_mov_b64_e32 v[54:55], 0
	v_mov_b64_e32 v[56:57], 0
	v_mov_b64_e32 v[58:59], 0
	v_mov_b64_e32 v[60:61], 0
	v_mov_b64_e32 v[62:63], 0
	v_mov_b64_e32 v[64:65], 0
	v_mov_b64_e32 v[66:67], 0
	v_mov_b64_e32 v[68:69], 0
	v_mov_b64_e32 v[70:71], 0
	v_mov_b64_e32 v[72:73], 0
	v_mov_b64_e32 v[74:75], 0
	v_mov_b64_e32 v[76:77], 0
	v_mov_b64_e32 v[78:79], 0
	v_mov_b64_e32 v[80:81], 0
	v_mov_b64_e32 v[82:83], 0
	v_mov_b64_e32 v[84:85], 0
	v_mov_b64_e32 v[86:87], 0
	v_mov_b64_e32 v[88:89], 0
	v_mov_b64_e32 v[90:91], 0
	v_mov_b64_e32 v[92:93], 0
	v_mov_b64_e32 v[94:95], 0
	v_mov_b64_e32 v[96:97], 0
	v_mov_b64_e32 v[98:99], 0
	v_mov_b64_e32 v[100:101], 0
	v_mov_b64_e32 v[102:103], 0
	v_mov_b64_e32 v[104:105], 0
	v_mov_b64_e32 v[106:107], 0
	v_mov_b64_e32 v[108:109], 0
	v_mov_b64_e32 v[110:111], 0
	v_mov_b64_e32 v[112:113], 0
	v_mov_b64_e32 v[114:115], 0
	v_mov_b64_e32 v[116:117], 0
	v_mov_b64_e32 v[118:119], 0
	v_mov_b64_e32 v[120:121], 0
	v_mov_b64_e32 v[122:123], 0
	v_mov_b64_e32 v[124:125], 0
	v_mov_b64_e32 v[126:127], 0
	v_mov_b64_e32 v[128:129], 0
	v_mov_b64_e32 v[130:131], 0
	v_add_u32_e32 v246, 0x10000, v1
	v_add_u32_e32 v247, 0x14000, v1
	v_add_u32_e32 v248, 0x18000, v1
	v_add_u32_e32 v249, 0x1c000, v1
.LBB0_246:
	s_add_i32 s76, s88, 2
	s_add_u32 s33, s0, 0xfff80080
	s_addc_u32 s48, s1, -1
	s_add_i32 m0, s35, 0xc000
	s_add_i32 s77, s35, 0xe000
	global_load_lds_dwordx4 v146, s[0:1]
	s_mov_b32 m0, s77
	s_cmp_eq_u32 vcc_hi, s88
	global_load_lds_dwordx4 v148, s[0:1]
	s_cselect_b32 s88, vcc_lo, s56
	s_cselect_b32 s91, s69, s48
	s_cselect_b32 s90, s75, s33
	s_cselect_b32 s89, s73, s57
	s_add_i32 s33, 0, 0x10000
	s_add_i32 s96, 0, 0x14000
	ds_read_b128 v[150:153], v246
	ds_read_b128 v[154:157], v246 offset:1024
	ds_read_b128 v[158:161], v246 offset:2048
	ds_read_b128 v[162:165], v246 offset:3072
	ds_read_b128 v[166:169], v247
	ds_read_b128 v[170:173], v247 offset:1024
	ds_read_b128 v[174:177], v247 offset:2048
	ds_read_b128 v[178:181], v247 offset:3072
	ds_read_b128 v[182:185], v141
	ds_read_b128 v[186:189], v141 offset:1024
	ds_read_b128 v[190:193], v141 offset:2048
	ds_read_b128 v[194:197], v141 offset:3072
	ds_read_b128 v[198:201], v141 offset:4096
	ds_read_b128 v[202:205], v141 offset:5120
	ds_read_b128 v[210:213], v141 offset:6144
	ds_read_b128 v[214:217], v141 offset:7168
	s_waitcnt vmcnt(8)
	s_waitcnt lgkmcnt(0)
	s_barrier
	s_setprio 1
	s_waitcnt lgkmcnt(0)
	v_mfma_f32_16x16x32_bf16 v[128:131], v[150:153], v[182:185], v[128:131]
	v_mfma_f32_16x16x32_bf16 v[124:127], v[158:161], v[182:185], v[124:127]
	v_mfma_f32_16x16x32_bf16 v[116:119], v[150:153], v[190:193], v[116:119]
	v_mfma_f32_16x16x32_bf16 v[108:111], v[158:161], v[190:193], v[108:111]
	v_mfma_f32_16x16x32_bf16 v[100:103], v[150:153], v[198:201], v[100:103]
	v_mfma_f32_16x16x32_bf16 v[92:95], v[158:161], v[198:201], v[92:95]
	v_mfma_f32_16x16x32_bf16 v[84:87], v[150:153], v[210:213], v[84:87]
	v_mfma_f32_16x16x32_bf16 v[76:79], v[158:161], v[210:213], v[76:79]
	v_mfma_f32_16x16x32_bf16 v[128:131], v[154:157], v[186:189], v[128:131]
	v_mfma_f32_16x16x32_bf16 v[124:127], v[162:165], v[186:189], v[124:127]
	v_mfma_f32_16x16x32_bf16 v[116:119], v[154:157], v[194:197], v[116:119]
	v_mfma_f32_16x16x32_bf16 v[108:111], v[162:165], v[194:197], v[108:111]
	v_mfma_f32_16x16x32_bf16 v[100:103], v[154:157], v[202:205], v[100:103]
	v_mfma_f32_16x16x32_bf16 v[92:95], v[162:165], v[202:205], v[92:95]
	v_mfma_f32_16x16x32_bf16 v[84:87], v[154:157], v[214:217], v[84:87]
	v_mfma_f32_16x16x32_bf16 v[76:79], v[162:165], v[214:217], v[76:79]
	s_setprio 0
	s_setprio 1
	v_mfma_f32_16x16x32_bf16 v[120:123], v[166:169], v[182:185], v[120:123]
	v_mfma_f32_16x16x32_bf16 v[112:115], v[174:177], v[182:185], v[112:115]
	v_mfma_f32_16x16x32_bf16 v[104:107], v[166:169], v[190:193], v[104:107]
	v_mfma_f32_16x16x32_bf16 v[96:99], v[174:177], v[190:193], v[96:99]
	v_mfma_f32_16x16x32_bf16 v[88:91], v[166:169], v[198:201], v[88:91]
	v_mfma_f32_16x16x32_bf16 v[80:83], v[174:177], v[198:201], v[80:83]
	v_mfma_f32_16x16x32_bf16 v[72:75], v[166:169], v[210:213], v[72:75]
	v_mfma_f32_16x16x32_bf16 v[68:71], v[174:177], v[210:213], v[68:71]
	v_mfma_f32_16x16x32_bf16 v[120:123], v[170:173], v[186:189], v[120:123]
	v_mfma_f32_16x16x32_bf16 v[112:115], v[178:181], v[186:189], v[112:115]
	v_mfma_f32_16x16x32_bf16 v[104:107], v[170:173], v[194:197], v[104:107]
	v_mfma_f32_16x16x32_bf16 v[96:99], v[178:181], v[194:197], v[96:99]
	v_mfma_f32_16x16x32_bf16 v[88:91], v[170:173], v[202:205], v[88:91]
	v_mfma_f32_16x16x32_bf16 v[80:83], v[178:181], v[202:205], v[80:83]
	v_mfma_f32_16x16x32_bf16 v[72:75], v[170:173], v[214:217], v[72:75]
	v_mfma_f32_16x16x32_bf16 v[68:71], v[178:181], v[214:217], v[68:71]
	s_setprio 0
	s_barrier
	s_add_i32 s48, s33, s29
	s_mov_b32 m0, s48
	s_nop 0
	global_load_lds_dwordx4 v134, s[88:89]
	s_add_i32 m0, s48, 0x2000
	s_add_u32 s78, s88, 0x80000
	s_addc_u32 s79, s89, 0
	s_add_i32 s48, s96, s29
	global_load_lds_dwordx4 v138, s[88:89]
	s_mov_b32 m0, s48
	s_nop 0
	global_load_lds_dwordx4 v134, s[78:79]
	s_add_i32 m0, s48, 0x2000
	s_nop 0
	global_load_lds_dwordx4 v138, s[78:79]
	s_mov_b32 m0, s35
	s_nop 0
	global_load_lds_dwordx4 v132, s[90:91]
	s_mov_b32 m0, s60
	s_nop 0
	global_load_lds_dwordx4 v136, s[90:91]
	ds_read_b128 v[182:185], v141 offset:16384
	ds_read_b128 v[186:189], v141 offset:17408
	ds_read_b128 v[190:193], v141 offset:18432
	ds_read_b128 v[194:197], v141 offset:19456
	ds_read_b128 v[198:201], v141 offset:20480
	ds_read_b128 v[202:205], v141 offset:21504
	ds_read_b128 v[210:213], v141 offset:22528
	ds_read_b128 v[214:217], v141 offset:23552
	s_waitcnt vmcnt(8)
	s_waitcnt lgkmcnt(0)
	s_barrier
	s_setprio 1
	s_waitcnt lgkmcnt(0)
	v_mfma_f32_16x16x32_bf16 v[64:67], v[150:153], v[182:185], v[64:67]
	v_mfma_f32_16x16x32_bf16 v[60:63], v[158:161], v[182:185], v[60:63]
	v_mfma_f32_16x16x32_bf16 v[52:55], v[150:153], v[190:193], v[52:55]
	v_mfma_f32_16x16x32_bf16 v[44:47], v[158:161], v[190:193], v[44:47]
	v_mfma_f32_16x16x32_bf16 v[36:39], v[150:153], v[198:201], v[36:39]
	v_mfma_f32_16x16x32_bf16 v[28:31], v[158:161], v[198:201], v[28:31]
	v_mfma_f32_16x16x32_bf16 v[20:23], v[150:153], v[210:213], v[20:23]
	v_mfma_f32_16x16x32_bf16 v[12:15], v[158:161], v[210:213], v[12:15]
	v_mfma_f32_16x16x32_bf16 v[64:67], v[154:157], v[186:189], v[64:67]
	v_mfma_f32_16x16x32_bf16 v[60:63], v[162:165], v[186:189], v[60:63]
	v_mfma_f32_16x16x32_bf16 v[52:55], v[154:157], v[194:197], v[52:55]
	v_mfma_f32_16x16x32_bf16 v[44:47], v[162:165], v[194:197], v[44:47]
	v_mfma_f32_16x16x32_bf16 v[36:39], v[154:157], v[202:205], v[36:39]
	v_mfma_f32_16x16x32_bf16 v[28:31], v[162:165], v[202:205], v[28:31]
	v_mfma_f32_16x16x32_bf16 v[20:23], v[154:157], v[214:217], v[20:23]
	v_mfma_f32_16x16x32_bf16 v[12:15], v[162:165], v[214:217], v[12:15]
	s_setprio 0
	s_setprio 1
	v_mfma_f32_16x16x32_bf16 v[56:59], v[166:169], v[182:185], v[56:59]
	v_mfma_f32_16x16x32_bf16 v[48:51], v[174:177], v[182:185], v[48:51]
	v_mfma_f32_16x16x32_bf16 v[40:43], v[166:169], v[190:193], v[40:43]
	v_mfma_f32_16x16x32_bf16 v[32:35], v[174:177], v[190:193], v[32:35]
	v_mfma_f32_16x16x32_bf16 v[24:27], v[166:169], v[198:201], v[24:27]
	v_mfma_f32_16x16x32_bf16 v[16:19], v[174:177], v[198:201], v[16:19]
	v_mfma_f32_16x16x32_bf16 v[8:11], v[166:169], v[210:213], v[8:11]
	v_mfma_f32_16x16x32_bf16 v[4:7], v[174:177], v[210:213], v[4:7]
	v_mfma_f32_16x16x32_bf16 v[56:59], v[170:173], v[186:189], v[56:59]
	v_mfma_f32_16x16x32_bf16 v[48:51], v[178:181], v[186:189], v[48:51]
	v_mfma_f32_16x16x32_bf16 v[40:43], v[170:173], v[194:197], v[40:43]
	v_mfma_f32_16x16x32_bf16 v[32:35], v[178:181], v[194:197], v[32:35]
	v_mfma_f32_16x16x32_bf16 v[24:27], v[170:173], v[202:205], v[24:27]
	v_mfma_f32_16x16x32_bf16 v[16:19], v[178:181], v[202:205], v[16:19]
	v_mfma_f32_16x16x32_bf16 v[8:11], v[170:173], v[214:217], v[8:11]
	v_mfma_f32_16x16x32_bf16 v[4:7], v[178:181], v[214:217], v[4:7]
	s_setprio 0
	s_barrier
	s_add_u32 s78, s90, 0x80000
	s_addc_u32 s79, s91, 0
	s_mov_b32 m0, s61
	s_nop 0
	global_load_lds_dwordx4 v132, s[78:79]
	s_mov_b32 m0, s62
	s_nop 0
	global_load_lds_dwordx4 v136, s[78:79]
	s_add_i32 s97, 0, 0x18000
	s_add_i32 s48, 0, 0x1c000
	ds_read_b128 v[150:153], v248
	ds_read_b128 v[154:157], v248 offset:1024
	ds_read_b128 v[158:161], v248 offset:2048
	ds_read_b128 v[162:165], v248 offset:3072
	ds_read_b128 v[166:169], v249
	ds_read_b128 v[170:173], v249 offset:1024
	ds_read_b128 v[174:177], v249 offset:2048
	ds_read_b128 v[178:181], v249 offset:3072
	ds_read_b128 v[182:185], v141 offset:32768
	ds_read_b128 v[186:189], v141 offset:33792
	ds_read_b128 v[190:193], v141 offset:34816
	ds_read_b128 v[194:197], v141 offset:35840
	ds_read_b128 v[198:201], v141 offset:36864
	ds_read_b128 v[202:205], v141 offset:37888
	ds_read_b128 v[210:213], v141 offset:38912
	ds_read_b128 v[214:217], v141 offset:39936
	s_waitcnt vmcnt(8)
	s_waitcnt lgkmcnt(0)
	s_barrier
	s_setprio 1
	s_waitcnt lgkmcnt(0)
	v_mfma_f32_16x16x32_bf16 v[128:131], v[150:153], v[182:185], v[128:131]
	v_mfma_f32_16x16x32_bf16 v[124:127], v[158:161], v[182:185], v[124:127]
	v_mfma_f32_16x16x32_bf16 v[116:119], v[150:153], v[190:193], v[116:119]
	v_mfma_f32_16x16x32_bf16 v[108:111], v[158:161], v[190:193], v[108:111]
	v_mfma_f32_16x16x32_bf16 v[100:103], v[150:153], v[198:201], v[100:103]
	v_mfma_f32_16x16x32_bf16 v[92:95], v[158:161], v[198:201], v[92:95]
	v_mfma_f32_16x16x32_bf16 v[84:87], v[150:153], v[210:213], v[84:87]
	v_mfma_f32_16x16x32_bf16 v[76:79], v[158:161], v[210:213], v[76:79]
	v_mfma_f32_16x16x32_bf16 v[128:131], v[154:157], v[186:189], v[128:131]
	v_mfma_f32_16x16x32_bf16 v[124:127], v[162:165], v[186:189], v[124:127]
	v_mfma_f32_16x16x32_bf16 v[116:119], v[154:157], v[194:197], v[116:119]
	v_mfma_f32_16x16x32_bf16 v[108:111], v[162:165], v[194:197], v[108:111]
	v_mfma_f32_16x16x32_bf16 v[100:103], v[154:157], v[202:205], v[100:103]
	v_mfma_f32_16x16x32_bf16 v[92:95], v[162:165], v[202:205], v[92:95]
	v_mfma_f32_16x16x32_bf16 v[84:87], v[154:157], v[214:217], v[84:87]
	v_mfma_f32_16x16x32_bf16 v[76:79], v[162:165], v[214:217], v[76:79]
	s_setprio 0
	s_setprio 1
	v_mfma_f32_16x16x32_bf16 v[120:123], v[166:169], v[182:185], v[120:123]
	v_mfma_f32_16x16x32_bf16 v[112:115], v[174:177], v[182:185], v[112:115]
	v_mfma_f32_16x16x32_bf16 v[104:107], v[166:169], v[190:193], v[104:107]
	v_mfma_f32_16x16x32_bf16 v[96:99], v[174:177], v[190:193], v[96:99]
	v_mfma_f32_16x16x32_bf16 v[88:91], v[166:169], v[198:201], v[88:91]
	v_mfma_f32_16x16x32_bf16 v[80:83], v[174:177], v[198:201], v[80:83]
	v_mfma_f32_16x16x32_bf16 v[72:75], v[166:169], v[210:213], v[72:75]
	v_mfma_f32_16x16x32_bf16 v[68:71], v[174:177], v[210:213], v[68:71]
	v_mfma_f32_16x16x32_bf16 v[120:123], v[170:173], v[186:189], v[120:123]
	v_mfma_f32_16x16x32_bf16 v[112:115], v[178:181], v[186:189], v[112:115]
	v_mfma_f32_16x16x32_bf16 v[104:107], v[170:173], v[194:197], v[104:107]
	v_mfma_f32_16x16x32_bf16 v[96:99], v[178:181], v[194:197], v[96:99]
	v_mfma_f32_16x16x32_bf16 v[88:91], v[170:173], v[202:205], v[88:91]
	v_mfma_f32_16x16x32_bf16 v[80:83], v[178:181], v[202:205], v[80:83]
	v_mfma_f32_16x16x32_bf16 v[72:75], v[170:173], v[214:217], v[72:75]
	v_mfma_f32_16x16x32_bf16 v[68:71], v[178:181], v[214:217], v[68:71]
	s_setprio 0
	s_barrier
	s_add_i32 s77, s97, s29
	s_mov_b32 m0, s77
	s_nop 0
	s_add_u32 s98, s88, 0x80
	s_addc_u32 s99, s89, 0
	s_nop 0
	global_load_lds_dwordx4 v134, s[98:99]
	s_add_i32 m0, s77, 0x2000
	s_add_u32 s78, s88, 0x80080
	s_addc_u32 s79, s89, 0
	s_add_i32 s77, s48, s29
	global_load_lds_dwordx4 v138, s[98:99]
	s_mov_b32 m0, s77
	s_nop 0
	global_load_lds_dwordx4 v134, s[78:79]
	s_add_i32 m0, s77, 0x2000
	s_nop 0
	global_load_lds_dwordx4 v138, s[78:79]
	s_mov_b32 m0, s63
	s_nop 0
	s_add_u32 s98, s90, 0x80
	s_addc_u32 s99, s91, 0
	s_nop 0
	global_load_lds_dwordx4 v132, s[98:99]
	s_mov_b32 m0, s64
	s_nop 0
	global_load_lds_dwordx4 v136, s[98:99]
	ds_read_b128 v[182:185], v141 offset:49152
	ds_read_b128 v[186:189], v141 offset:50176
	ds_read_b128 v[190:193], v141 offset:51200
	ds_read_b128 v[194:197], v141 offset:52224
	ds_read_b128 v[198:201], v141 offset:53248
	ds_read_b128 v[202:205], v141 offset:54272
	ds_read_b128 v[210:213], v141 offset:55296
	ds_read_b128 v[214:217], v141 offset:56320
	s_waitcnt vmcnt(8)
	s_waitcnt lgkmcnt(0)
	s_barrier
	s_setprio 1
	s_waitcnt lgkmcnt(0)
	v_mfma_f32_16x16x32_bf16 v[64:67], v[150:153], v[182:185], v[64:67]
	v_mfma_f32_16x16x32_bf16 v[60:63], v[158:161], v[182:185], v[60:63]
	v_mfma_f32_16x16x32_bf16 v[52:55], v[150:153], v[190:193], v[52:55]
	v_mfma_f32_16x16x32_bf16 v[44:47], v[158:161], v[190:193], v[44:47]
	v_mfma_f32_16x16x32_bf16 v[36:39], v[150:153], v[198:201], v[36:39]
	v_mfma_f32_16x16x32_bf16 v[28:31], v[158:161], v[198:201], v[28:31]
	v_mfma_f32_16x16x32_bf16 v[20:23], v[150:153], v[210:213], v[20:23]
	v_mfma_f32_16x16x32_bf16 v[12:15], v[158:161], v[210:213], v[12:15]
	v_mfma_f32_16x16x32_bf16 v[64:67], v[154:157], v[186:189], v[64:67]
	v_mfma_f32_16x16x32_bf16 v[60:63], v[162:165], v[186:189], v[60:63]
	v_mfma_f32_16x16x32_bf16 v[52:55], v[154:157], v[194:197], v[52:55]
	v_mfma_f32_16x16x32_bf16 v[44:47], v[162:165], v[194:197], v[44:47]
	v_mfma_f32_16x16x32_bf16 v[36:39], v[154:157], v[202:205], v[36:39]
	v_mfma_f32_16x16x32_bf16 v[28:31], v[162:165], v[202:205], v[28:31]
	v_mfma_f32_16x16x32_bf16 v[20:23], v[154:157], v[214:217], v[20:23]
	v_mfma_f32_16x16x32_bf16 v[12:15], v[162:165], v[214:217], v[12:15]
	s_setprio 0
	s_setprio 1
	v_mfma_f32_16x16x32_bf16 v[56:59], v[166:169], v[182:185], v[56:59]
	v_mfma_f32_16x16x32_bf16 v[48:51], v[174:177], v[182:185], v[48:51]
	v_mfma_f32_16x16x32_bf16 v[40:43], v[166:169], v[190:193], v[40:43]
	v_mfma_f32_16x16x32_bf16 v[32:35], v[174:177], v[190:193], v[32:35]
	v_mfma_f32_16x16x32_bf16 v[24:27], v[166:169], v[198:201], v[24:27]
	v_mfma_f32_16x16x32_bf16 v[16:19], v[174:177], v[198:201], v[16:19]
	v_mfma_f32_16x16x32_bf16 v[8:11], v[166:169], v[210:213], v[8:11]
	v_mfma_f32_16x16x32_bf16 v[4:7], v[174:177], v[210:213], v[4:7]
	v_mfma_f32_16x16x32_bf16 v[56:59], v[170:173], v[186:189], v[56:59]
	v_mfma_f32_16x16x32_bf16 v[48:51], v[178:181], v[186:189], v[48:51]
	v_mfma_f32_16x16x32_bf16 v[40:43], v[170:173], v[194:197], v[40:43]
	v_mfma_f32_16x16x32_bf16 v[32:35], v[178:181], v[194:197], v[32:35]
	v_mfma_f32_16x16x32_bf16 v[24:27], v[170:173], v[202:205], v[24:27]
	v_mfma_f32_16x16x32_bf16 v[16:19], v[178:181], v[202:205], v[16:19]
	v_mfma_f32_16x16x32_bf16 v[8:11], v[170:173], v[214:217], v[8:11]
	v_mfma_f32_16x16x32_bf16 v[4:7], v[178:181], v[214:217], v[4:7]
	s_setprio 0
	s_barrier
	s_add_u32 s0, s0, 0x100
	s_addc_u32 s1, s1, 0
	s_add_u32 s56, s56, 0x100
	s_addc_u32 s57, s57, 0
	s_cmp_ge_i32 s76, s55
	s_mov_b32 s88, s76
	s_cbranch_scc0 .LBB0_246
	s_and_b64 vcc, exec, s[58:59]
	s_cbranch_vccz .LBB0_249
	s_barrier

.LBB0_520:
	s_add_i32 s9, s64, -2
	s_add_u32 s74, s74, 0x80080
	s_addc_u32 s75, s75, 0
	s_add_u32 s23, s84, 0x100
	s_addc_u32 s35, s85, 0
	s_mov_b32 s54, 0
	v_mov_b64_e32 v[4:5], 0
	v_mov_b64_e32 v[6:7], 0
	v_mov_b64_e32 v[8:9], 0
	v_mov_b64_e32 v[10:11], 0
	v_mov_b64_e32 v[12:13], 0
	v_mov_b64_e32 v[14:15], 0
	v_mov_b64_e32 v[16:17], 0
	v_mov_b64_e32 v[18:19], 0
	v_mov_b64_e32 v[20:21], 0
	v_mov_b64_e32 v[22:23], 0
	v_mov_b64_e32 v[24:25], 0
	v_mov_b64_e32 v[26:27], 0
	v_mov_b64_e32 v[28:29], 0
	v_mov_b64_e32 v[30:31], 0
	v_mov_b64_e32 v[32:33], 0
	v_mov_b64_e32 v[34:35], 0
	v_mov_b64_e32 v[36:37], 0
	v_mov_b64_e32 v[38:39], 0
	v_mov_b64_e32 v[40:41], 0
	v_mov_b64_e32 v[42:43], 0
	v_mov_b64_e32 v[44:45], 0
	v_mov_b64_e32 v[46:47], 0
	v_mov_b64_e32 v[48:49], 0
	v_mov_b64_e32 v[50:51], 0
	v_mov_b64_e32 v[52:53], 0
	v_mov_b64_e32 v[54:55], 0
	v_mov_b64_e32 v[56:57], 0
	v_mov_b64_e32 v[58:59], 0
	v_mov_b64_e32 v[60:61], 0
	v_mov_b64_e32 v[62:63], 0
	v_mov_b64_e32 v[64:65], 0
	v_mov_b64_e32 v[66:67], 0
	v_mov_b64_e32 v[68:69], 0
	v_mov_b64_e32 v[70:71], 0
	v_mov_b64_e32 v[72:73], 0
	v_mov_b64_e32 v[74:75], 0
	v_mov_b64_e32 v[76:77], 0
	v_mov_b64_e32 v[78:79], 0
	v_mov_b64_e32 v[80:81], 0
	v_mov_b64_e32 v[82:83], 0
	v_mov_b64_e32 v[84:85], 0
	v_mov_b64_e32 v[86:87], 0
	v_mov_b64_e32 v[88:89], 0
	v_mov_b64_e32 v[90:91], 0
	v_mov_b64_e32 v[92:93], 0
	v_mov_b64_e32 v[94:95], 0
	v_mov_b64_e32 v[96:97], 0
	v_mov_b64_e32 v[98:99], 0
	v_mov_b64_e32 v[100:101], 0
	v_mov_b64_e32 v[102:103], 0
	v_mov_b64_e32 v[104:105], 0
	v_mov_b64_e32 v[106:107], 0
	v_mov_b64_e32 v[108:109], 0
	v_mov_b64_e32 v[110:111], 0
	v_mov_b64_e32 v[112:113], 0
	v_mov_b64_e32 v[114:115], 0
	v_mov_b64_e32 v[116:117], 0
	v_mov_b64_e32 v[118:119], 0
	v_mov_b64_e32 v[120:121], 0
	v_mov_b64_e32 v[122:123], 0
	v_mov_b64_e32 v[124:125], 0
	v_mov_b64_e32 v[126:127], 0
	v_mov_b64_e32 v[128:129], 0
	v_mov_b64_e32 v[130:131], 0
	v_add_u32_e32 v246, 0x10000, v142
	v_add_u32_e32 v247, 0x14000, v142
	v_add_u32_e32 v248, 0x18000, v142
	v_add_u32_e32 v249, 0x1c000, v142
.LBB0_521:
	s_add_i32 s55, s54, 2
	s_add_u32 s56, s74, 0xfff80080
	s_addc_u32 s57, s75, -1
	s_add_i32 m0, s17, 0xc000
	s_add_i32 s76, s17, 0xe000
	global_load_lds_dwordx4 v138, s[74:75]
	s_mov_b32 m0, s76
	s_cmp_eq_u32 s9, s54
	global_load_lds_dwordx4 v140, s[74:75]
	s_cselect_b32 s87, s69, s57
	s_cselect_b32 s86, s68, s56
	s_cselect_b32 s85, s73, s35
	s_cselect_b32 s84, s72, s23
	ds_read_b128 v[146:149], v246
	ds_read_b128 v[150:153], v246 offset:1024
	ds_read_b128 v[154:157], v246 offset:2048
	ds_read_b128 v[158:161], v246 offset:3072
	ds_read_b128 v[162:165], v247
	ds_read_b128 v[166:169], v247 offset:1024
	ds_read_b128 v[170:173], v247 offset:2048
	ds_read_b128 v[174:177], v247 offset:3072
	ds_read_b128 v[178:181], v144
	ds_read_b128 v[182:185], v144 offset:1024
	ds_read_b128 v[186:189], v144 offset:2048
	ds_read_b128 v[190:193], v144 offset:3072
	ds_read_b128 v[194:197], v144 offset:4096
	ds_read_b128 v[198:201], v144 offset:5120
	ds_read_b128 v[202:205], v144 offset:6144
	ds_read_b128 v[210:213], v144 offset:7168
	s_waitcnt vmcnt(8)
	s_waitcnt lgkmcnt(0)
	s_barrier
	s_setprio 1
	s_waitcnt lgkmcnt(0)
	v_mfma_f32_16x16x32_bf16 v[128:131], v[146:149], v[178:181], v[128:131]
	v_mfma_f32_16x16x32_bf16 v[124:127], v[154:157], v[178:181], v[124:127]
	v_mfma_f32_16x16x32_bf16 v[120:123], v[146:149], v[186:189], v[120:123]
	v_mfma_f32_16x16x32_bf16 v[116:119], v[154:157], v[186:189], v[116:119]
	v_mfma_f32_16x16x32_bf16 v[104:107], v[146:149], v[194:197], v[104:107]
	v_mfma_f32_16x16x32_bf16 v[100:103], v[154:157], v[194:197], v[100:103]
	v_mfma_f32_16x16x32_bf16 v[88:91], v[146:149], v[202:205], v[88:91]
	v_mfma_f32_16x16x32_bf16 v[84:87], v[154:157], v[202:205], v[84:87]
	v_mfma_f32_16x16x32_bf16 v[128:131], v[150:153], v[182:185], v[128:131]
	v_mfma_f32_16x16x32_bf16 v[124:127], v[158:161], v[182:185], v[124:127]
	v_mfma_f32_16x16x32_bf16 v[120:123], v[150:153], v[190:193], v[120:123]
	v_mfma_f32_16x16x32_bf16 v[116:119], v[158:161], v[190:193], v[116:119]
	v_mfma_f32_16x16x32_bf16 v[104:107], v[150:153], v[198:201], v[104:107]
	v_mfma_f32_16x16x32_bf16 v[100:103], v[158:161], v[198:201], v[100:103]
	v_mfma_f32_16x16x32_bf16 v[88:91], v[150:153], v[210:213], v[88:91]
	v_mfma_f32_16x16x32_bf16 v[84:87], v[158:161], v[210:213], v[84:87]
	s_setprio 0
	s_setprio 1
	v_mfma_f32_16x16x32_bf16 v[112:115], v[162:165], v[178:181], v[112:115]
	v_mfma_f32_16x16x32_bf16 v[108:111], v[170:173], v[178:181], v[108:111]
	v_mfma_f32_16x16x32_bf16 v[96:99], v[162:165], v[186:189], v[96:99]
	v_mfma_f32_16x16x32_bf16 v[92:95], v[170:173], v[186:189], v[92:95]
	v_mfma_f32_16x16x32_bf16 v[80:83], v[162:165], v[194:197], v[80:83]
	v_mfma_f32_16x16x32_bf16 v[76:79], v[170:173], v[194:197], v[76:79]
	v_mfma_f32_16x16x32_bf16 v[72:75], v[162:165], v[202:205], v[72:75]
	v_mfma_f32_16x16x32_bf16 v[68:71], v[170:173], v[202:205], v[68:71]
	v_mfma_f32_16x16x32_bf16 v[112:115], v[166:169], v[182:185], v[112:115]
	v_mfma_f32_16x16x32_bf16 v[108:111], v[174:177], v[182:185], v[108:111]
	v_mfma_f32_16x16x32_bf16 v[96:99], v[166:169], v[190:193], v[96:99]
	v_mfma_f32_16x16x32_bf16 v[92:95], v[174:177], v[190:193], v[92:95]
	v_mfma_f32_16x16x32_bf16 v[80:83], v[166:169], v[198:201], v[80:83]
	v_mfma_f32_16x16x32_bf16 v[76:79], v[174:177], v[198:201], v[76:79]
	v_mfma_f32_16x16x32_bf16 v[72:75], v[166:169], v[210:213], v[72:75]
	v_mfma_f32_16x16x32_bf16 v[68:71], v[174:177], v[210:213], v[68:71]
	s_setprio 0
	s_barrier
	s_add_i32 s54, s33, s16
	s_mov_b32 m0, s54
	s_nop 0
	global_load_lds_dwordx4 v2, s[84:85]
	s_add_i32 m0, s54, 0x2000
	s_add_u32 s56, s84, 0x80000
	s_addc_u32 s57, s85, 0
	s_add_i32 s54, s96, s16
	global_load_lds_dwordx4 v136, s[84:85]
	s_mov_b32 m0, s54
	s_nop 0
	global_load_lds_dwordx4 v2, s[56:57]
	s_add_i32 m0, s54, 0x2000
	s_nop 0
	global_load_lds_dwordx4 v136, s[56:57]
	s_mov_b32 m0, s17
	s_nop 0
	global_load_lds_dwordx4 v132, s[86:87]
	s_mov_b32 m0, s29
	s_nop 0
	global_load_lds_dwordx4 v134, s[86:87]
	ds_read_b128 v[178:181], v144 offset:16384
	ds_read_b128 v[182:185], v144 offset:17408
	ds_read_b128 v[186:189], v144 offset:18432
	ds_read_b128 v[190:193], v144 offset:19456
	ds_read_b128 v[194:197], v144 offset:20480
	ds_read_b128 v[198:201], v144 offset:21504
	ds_read_b128 v[202:205], v144 offset:22528
	ds_read_b128 v[210:213], v144 offset:23552
	s_waitcnt vmcnt(8)
	s_waitcnt lgkmcnt(0)
	s_barrier
	s_setprio 1
	s_waitcnt lgkmcnt(0)
	v_mfma_f32_16x16x32_bf16 v[64:67], v[146:149], v[178:181], v[64:67]
	v_mfma_f32_16x16x32_bf16 v[60:63], v[154:157], v[178:181], v[60:63]
	v_mfma_f32_16x16x32_bf16 v[56:59], v[146:149], v[186:189], v[56:59]
	v_mfma_f32_16x16x32_bf16 v[52:55], v[154:157], v[186:189], v[52:55]
	v_mfma_f32_16x16x32_bf16 v[40:43], v[146:149], v[194:197], v[40:43]
	v_mfma_f32_16x16x32_bf16 v[36:39], v[154:157], v[194:197], v[36:39]
	v_mfma_f32_16x16x32_bf16 v[24:27], v[146:149], v[202:205], v[24:27]
	v_mfma_f32_16x16x32_bf16 v[20:23], v[154:157], v[202:205], v[20:23]
	v_mfma_f32_16x16x32_bf16 v[64:67], v[150:153], v[182:185], v[64:67]
	v_mfma_f32_16x16x32_bf16 v[60:63], v[158:161], v[182:185], v[60:63]
	v_mfma_f32_16x16x32_bf16 v[56:59], v[150:153], v[190:193], v[56:59]
	v_mfma_f32_16x16x32_bf16 v[52:55], v[158:161], v[190:193], v[52:55]
	v_mfma_f32_16x16x32_bf16 v[40:43], v[150:153], v[198:201], v[40:43]
	v_mfma_f32_16x16x32_bf16 v[36:39], v[158:161], v[198:201], v[36:39]
	v_mfma_f32_16x16x32_bf16 v[24:27], v[150:153], v[210:213], v[24:27]
	v_mfma_f32_16x16x32_bf16 v[20:23], v[158:161], v[210:213], v[20:23]
	s_setprio 0
	s_setprio 1
	v_mfma_f32_16x16x32_bf16 v[48:51], v[162:165], v[178:181], v[48:51]
	v_mfma_f32_16x16x32_bf16 v[44:47], v[170:173], v[178:181], v[44:47]
	v_mfma_f32_16x16x32_bf16 v[32:35], v[162:165], v[186:189], v[32:35]
	v_mfma_f32_16x16x32_bf16 v[28:31], v[170:173], v[186:189], v[28:31]
	v_mfma_f32_16x16x32_bf16 v[16:19], v[162:165], v[194:197], v[16:19]
	v_mfma_f32_16x16x32_bf16 v[12:15], v[170:173], v[194:197], v[12:15]
	v_mfma_f32_16x16x32_bf16 v[8:11], v[162:165], v[202:205], v[8:11]
	v_mfma_f32_16x16x32_bf16 v[4:7], v[170:173], v[202:205], v[4:7]
	v_mfma_f32_16x16x32_bf16 v[48:51], v[166:169], v[182:185], v[48:51]
	v_mfma_f32_16x16x32_bf16 v[44:47], v[174:177], v[182:185], v[44:47]
	v_mfma_f32_16x16x32_bf16 v[32:35], v[166:169], v[190:193], v[32:35]
	v_mfma_f32_16x16x32_bf16 v[28:31], v[174:177], v[190:193], v[28:31]
	v_mfma_f32_16x16x32_bf16 v[16:19], v[166:169], v[198:201], v[16:19]
	v_mfma_f32_16x16x32_bf16 v[12:15], v[174:177], v[198:201], v[12:15]
	v_mfma_f32_16x16x32_bf16 v[8:11], v[166:169], v[210:213], v[8:11]
	v_mfma_f32_16x16x32_bf16 v[4:7], v[174:177], v[210:213], v[4:7]
	s_setprio 0
	s_barrier
	s_add_u32 s56, s86, 0x80000
	s_addc_u32 s57, s87, 0
	s_mov_b32 m0, s60
	s_nop 0
	global_load_lds_dwordx4 v132, s[56:57]
	s_mov_b32 m0, s61
	s_nop 0
	global_load_lds_dwordx4 v134, s[56:57]
	ds_read_b128 v[146:149], v248
	ds_read_b128 v[150:153], v248 offset:1024
	ds_read_b128 v[154:157], v248 offset:2048
	ds_read_b128 v[158:161], v248 offset:3072
	ds_read_b128 v[162:165], v249
	ds_read_b128 v[166:169], v249 offset:1024
	ds_read_b128 v[170:173], v249 offset:2048
	ds_read_b128 v[174:177], v249 offset:3072
	ds_read_b128 v[178:181], v144 offset:32768
	ds_read_b128 v[182:185], v144 offset:33792
	ds_read_b128 v[186:189], v144 offset:34816
	ds_read_b128 v[190:193], v144 offset:35840
	ds_read_b128 v[194:197], v144 offset:36864
	ds_read_b128 v[198:201], v144 offset:37888
	ds_read_b128 v[202:205], v144 offset:38912
	ds_read_b128 v[210:213], v144 offset:39936
	s_waitcnt vmcnt(8)
	s_waitcnt lgkmcnt(0)
	s_barrier
	s_setprio 1
	s_waitcnt lgkmcnt(0)
	v_mfma_f32_16x16x32_bf16 v[128:131], v[146:149], v[178:181], v[128:131]
	v_mfma_f32_16x16x32_bf16 v[124:127], v[154:157], v[178:181], v[124:127]
	v_mfma_f32_16x16x32_bf16 v[120:123], v[146:149], v[186:189], v[120:123]
	v_mfma_f32_16x16x32_bf16 v[116:119], v[154:157], v[186:189], v[116:119]
	v_mfma_f32_16x16x32_bf16 v[104:107], v[146:149], v[194:197], v[104:107]
	v_mfma_f32_16x16x32_bf16 v[100:103], v[154:157], v[194:197], v[100:103]
	v_mfma_f32_16x16x32_bf16 v[88:91], v[146:149], v[202:205], v[88:91]
	v_mfma_f32_16x16x32_bf16 v[84:87], v[154:157], v[202:205], v[84:87]
	v_mfma_f32_16x16x32_bf16 v[128:131], v[150:153], v[182:185], v[128:131]
	v_mfma_f32_16x16x32_bf16 v[124:127], v[158:161], v[182:185], v[124:127]
	v_mfma_f32_16x16x32_bf16 v[120:123], v[150:153], v[190:193], v[120:123]
	v_mfma_f32_16x16x32_bf16 v[116:119], v[158:161], v[190:193], v[116:119]
	v_mfma_f32_16x16x32_bf16 v[104:107], v[150:153], v[198:201], v[104:107]
	v_mfma_f32_16x16x32_bf16 v[100:103], v[158:161], v[198:201], v[100:103]
	v_mfma_f32_16x16x32_bf16 v[88:91], v[150:153], v[210:213], v[88:91]
	v_mfma_f32_16x16x32_bf16 v[84:87], v[158:161], v[210:213], v[84:87]
	s_setprio 0
	s_setprio 1
	v_mfma_f32_16x16x32_bf16 v[112:115], v[162:165], v[178:181], v[112:115]
	v_mfma_f32_16x16x32_bf16 v[108:111], v[170:173], v[178:181], v[108:111]
	v_mfma_f32_16x16x32_bf16 v[96:99], v[162:165], v[186:189], v[96:99]
	v_mfma_f32_16x16x32_bf16 v[92:95], v[170:173], v[186:189], v[92:95]
	v_mfma_f32_16x16x32_bf16 v[80:83], v[162:165], v[194:197], v[80:83]
	v_mfma_f32_16x16x32_bf16 v[76:79], v[170:173], v[194:197], v[76:79]
	v_mfma_f32_16x16x32_bf16 v[72:75], v[162:165], v[202:205], v[72:75]
	v_mfma_f32_16x16x32_bf16 v[68:71], v[170:173], v[202:205], v[68:71]
	v_mfma_f32_16x16x32_bf16 v[112:115], v[166:169], v[182:185], v[112:115]
	v_mfma_f32_16x16x32_bf16 v[108:111], v[174:177], v[182:185], v[108:111]
	v_mfma_f32_16x16x32_bf16 v[96:99], v[166:169], v[190:193], v[96:99]
	v_mfma_f32_16x16x32_bf16 v[92:95], v[174:177], v[190:193], v[92:95]
	v_mfma_f32_16x16x32_bf16 v[80:83], v[166:169], v[198:201], v[80:83]
	v_mfma_f32_16x16x32_bf16 v[76:79], v[174:177], v[198:201], v[76:79]
	v_mfma_f32_16x16x32_bf16 v[72:75], v[166:169], v[210:213], v[72:75]
	v_mfma_f32_16x16x32_bf16 v[68:71], v[174:177], v[210:213], v[68:71]
	s_setprio 0
	s_barrier
	s_add_i32 s54, s97, s16
	s_mov_b32 m0, s54
	s_nop 0
	s_add_u32 s98, s84, 0x80
	s_addc_u32 s99, s85, 0
	s_nop 0
	global_load_lds_dwordx4 v2, s[98:99]
	s_add_i32 m0, s54, 0x2000
	s_add_u32 s56, s84, 0x80080
	s_addc_u32 s57, s85, 0
	s_add_i32 s54, s48, s16
	global_load_lds_dwordx4 v136, s[98:99]
	s_mov_b32 m0, s54
	s_nop 0
	global_load_lds_dwordx4 v2, s[56:57]
	s_add_i32 m0, s54, 0x2000
	s_nop 0
	global_load_lds_dwordx4 v136, s[56:57]
	s_mov_b32 m0, s62
	s_nop 0
	s_add_u32 s98, s86, 0x80
	s_addc_u32 s99, s87, 0
	s_nop 0
	global_load_lds_dwordx4 v132, s[98:99]
	s_mov_b32 m0, s63
	s_nop 0
	global_load_lds_dwordx4 v134, s[98:99]
	ds_read_b128 v[178:181], v144 offset:49152
	ds_read_b128 v[182:185], v144 offset:50176
	ds_read_b128 v[186:189], v144 offset:51200
	ds_read_b128 v[190:193], v144 offset:52224
	ds_read_b128 v[194:197], v144 offset:53248
	ds_read_b128 v[198:201], v144 offset:54272
	ds_read_b128 v[202:205], v144 offset:55296
	ds_read_b128 v[210:213], v144 offset:56320
	s_waitcnt vmcnt(8)
	s_waitcnt lgkmcnt(0)
	s_barrier
	s_setprio 1
	s_waitcnt lgkmcnt(0)
	v_mfma_f32_16x16x32_bf16 v[64:67], v[146:149], v[178:181], v[64:67]
	v_mfma_f32_16x16x32_bf16 v[60:63], v[154:157], v[178:181], v[60:63]
	v_mfma_f32_16x16x32_bf16 v[56:59], v[146:149], v[186:189], v[56:59]
	v_mfma_f32_16x16x32_bf16 v[52:55], v[154:157], v[186:189], v[52:55]
	v_mfma_f32_16x16x32_bf16 v[40:43], v[146:149], v[194:197], v[40:43]
	v_mfma_f32_16x16x32_bf16 v[36:39], v[154:157], v[194:197], v[36:39]
	v_mfma_f32_16x16x32_bf16 v[24:27], v[146:149], v[202:205], v[24:27]
	v_mfma_f32_16x16x32_bf16 v[20:23], v[154:157], v[202:205], v[20:23]
	v_mfma_f32_16x16x32_bf16 v[64:67], v[150:153], v[182:185], v[64:67]
	v_mfma_f32_16x16x32_bf16 v[60:63], v[158:161], v[182:185], v[60:63]
	v_mfma_f32_16x16x32_bf16 v[56:59], v[150:153], v[190:193], v[56:59]
	v_mfma_f32_16x16x32_bf16 v[52:55], v[158:161], v[190:193], v[52:55]
	v_mfma_f32_16x16x32_bf16 v[40:43], v[150:153], v[198:201], v[40:43]
	v_mfma_f32_16x16x32_bf16 v[36:39], v[158:161], v[198:201], v[36:39]
	v_mfma_f32_16x16x32_bf16 v[24:27], v[150:153], v[210:213], v[24:27]
	v_mfma_f32_16x16x32_bf16 v[20:23], v[158:161], v[210:213], v[20:23]
	s_setprio 0
	s_setprio 1
	v_mfma_f32_16x16x32_bf16 v[48:51], v[162:165], v[178:181], v[48:51]
	v_mfma_f32_16x16x32_bf16 v[44:47], v[170:173], v[178:181], v[44:47]
	v_mfma_f32_16x16x32_bf16 v[32:35], v[162:165], v[186:189], v[32:35]
	v_mfma_f32_16x16x32_bf16 v[28:31], v[170:173], v[186:189], v[28:31]
	v_mfma_f32_16x16x32_bf16 v[16:19], v[162:165], v[194:197], v[16:19]
	v_mfma_f32_16x16x32_bf16 v[12:15], v[170:173], v[194:197], v[12:15]
	v_mfma_f32_16x16x32_bf16 v[8:11], v[162:165], v[202:205], v[8:11]
	v_mfma_f32_16x16x32_bf16 v[4:7], v[170:173], v[202:205], v[4:7]
	v_mfma_f32_16x16x32_bf16 v[48:51], v[166:169], v[182:185], v[48:51]
	v_mfma_f32_16x16x32_bf16 v[44:47], v[174:177], v[182:185], v[44:47]
	v_mfma_f32_16x16x32_bf16 v[32:35], v[166:169], v[190:193], v[32:35]
	v_mfma_f32_16x16x32_bf16 v[28:31], v[174:177], v[190:193], v[28:31]
	v_mfma_f32_16x16x32_bf16 v[16:19], v[166:169], v[198:201], v[16:19]
	v_mfma_f32_16x16x32_bf16 v[12:15], v[174:177], v[198:201], v[12:15]
	v_mfma_f32_16x16x32_bf16 v[8:11], v[166:169], v[210:213], v[8:11]
	v_mfma_f32_16x16x32_bf16 v[4:7], v[174:177], v[210:213], v[4:7]
	s_setprio 0
	s_barrier
	s_add_u32 s74, s74, 0x100
	s_addc_u32 s75, s75, 0
	s_add_u32 s23, s23, 0x100
	s_addc_u32 s35, s35, 0
	s_cmp_ge_u32 s55, s64
	s_mov_b32 s54, s55
	s_cbranch_scc0 .LBB0_521
	s_and_b64 vcc, exec, s[58:59]
	s_cbranch_vccz .LBB0_524
	s_barrier

.LBB0_693:
	s_ashr_i32 s75, s74, 31
	s_lshl_b64 s[16:17], s[74:75], 20
	s_add_u32 s84, s14, s16
	s_addc_u32 s85, s15, s17
	s_and_b64 s[16:17], s[36:37], exec
	s_cselect_b32 s16, s85, s89
	s_cselect_b32 s17, s84, s88
	s_ashr_i32 s73, s72, 31
	s_lshl_b64 s[50:51], s[72:73], 20
	s_add_u32 s86, s23, s50
	s_addc_u32 s87, s29, s51
	s_and_b64 s[50:51], s[36:37], exec
	s_cselect_b32 s50, s87, s91
	s_cselect_b32 s51, s86, s90
	s_add_u32 s88, s88, 0x80080
	s_addc_u32 s89, s89, 0
	s_add_u32 s54, s90, 0x100
	s_addc_u32 s55, s91, 0
	s_mov_b32 s56, -2
	v_mov_b64_e32 v[4:5], 0
	v_mov_b64_e32 v[6:7], 0
	v_mov_b64_e32 v[8:9], 0
	v_mov_b64_e32 v[10:11], 0
	v_mov_b64_e32 v[12:13], 0
	v_mov_b64_e32 v[14:15], 0
	v_mov_b64_e32 v[16:17], 0
	v_mov_b64_e32 v[18:19], 0
	v_mov_b64_e32 v[20:21], 0
	v_mov_b64_e32 v[22:23], 0
	v_mov_b64_e32 v[24:25], 0
	v_mov_b64_e32 v[26:27], 0
	v_mov_b64_e32 v[28:29], 0
	v_mov_b64_e32 v[30:31], 0
	v_mov_b64_e32 v[32:33], 0
	v_mov_b64_e32 v[34:35], 0
	v_mov_b64_e32 v[36:37], 0
	v_mov_b64_e32 v[38:39], 0
	v_mov_b64_e32 v[40:41], 0
	v_mov_b64_e32 v[42:43], 0
	v_mov_b64_e32 v[44:45], 0
	v_mov_b64_e32 v[46:47], 0
	v_mov_b64_e32 v[48:49], 0
	v_mov_b64_e32 v[50:51], 0
	v_mov_b64_e32 v[52:53], 0
	v_mov_b64_e32 v[54:55], 0
	v_mov_b64_e32 v[56:57], 0
	v_mov_b64_e32 v[58:59], 0
	v_mov_b64_e32 v[60:61], 0
	v_mov_b64_e32 v[62:63], 0
	v_mov_b64_e32 v[64:65], 0
	v_mov_b64_e32 v[66:67], 0
	v_mov_b64_e32 v[68:69], 0
	v_mov_b64_e32 v[70:71], 0
	v_mov_b64_e32 v[72:73], 0
	v_mov_b64_e32 v[74:75], 0
	v_mov_b64_e32 v[76:77], 0
	v_mov_b64_e32 v[78:79], 0
	v_mov_b64_e32 v[80:81], 0
	v_mov_b64_e32 v[82:83], 0
	v_mov_b64_e32 v[84:85], 0
	v_mov_b64_e32 v[86:87], 0
	v_mov_b64_e32 v[88:89], 0
	v_mov_b64_e32 v[90:91], 0
	v_mov_b64_e32 v[92:93], 0
	v_mov_b64_e32 v[94:95], 0
	v_mov_b64_e32 v[96:97], 0
	v_mov_b64_e32 v[98:99], 0
	v_mov_b64_e32 v[100:101], 0
	v_mov_b64_e32 v[102:103], 0
	v_mov_b64_e32 v[104:105], 0
	v_mov_b64_e32 v[106:107], 0
	v_mov_b64_e32 v[108:109], 0
	v_mov_b64_e32 v[110:111], 0
	v_mov_b64_e32 v[112:113], 0
	v_mov_b64_e32 v[114:115], 0
	v_mov_b64_e32 v[116:117], 0
	v_mov_b64_e32 v[118:119], 0
	v_mov_b64_e32 v[120:121], 0
	v_mov_b64_e32 v[122:123], 0
	v_mov_b64_e32 v[124:125], 0
	v_mov_b64_e32 v[126:127], 0
	v_mov_b64_e32 v[128:129], 0
	v_mov_b64_e32 v[130:131], 0
	v_add_u32_e32 v246, 0x10000, v144
	v_add_u32_e32 v247, 0x14000, v144
	v_add_u32_e32 v248, 0x18000, v144
	v_add_u32_e32 v249, 0x1c000, v144
.LBB0_694:
	s_add_u32 s57, s88, 0xfff80080
	s_addc_u32 s73, s89, -1
	s_add_i32 m0, s60, 0xc000
	s_add_i32 s75, s60, 0xe000
	global_load_lds_dwordx4 v138, s[88:89]
	s_mov_b32 m0, s75
	s_cmp_eq_u32 s56, 28
	global_load_lds_dwordx4 v140, s[88:89]
	s_cselect_b32 vcc_hi, s16, s73
	s_cselect_b32 vcc_lo, s17, s57
	s_cselect_b32 s91, s50, s55
	s_cselect_b32 s90, s51, s54
	ds_read_b128 v[148:151], v246
	ds_read_b128 v[152:155], v246 offset:1024
	ds_read_b128 v[156:159], v246 offset:2048
	ds_read_b128 v[160:163], v246 offset:3072
	ds_read_b128 v[164:167], v247
	ds_read_b128 v[168:171], v247 offset:1024
	ds_read_b128 v[172:175], v247 offset:2048
	ds_read_b128 v[176:179], v247 offset:3072
	ds_read_b128 v[180:183], v146
	ds_read_b128 v[184:187], v146 offset:1024
	ds_read_b128 v[188:191], v146 offset:2048
	ds_read_b128 v[192:195], v146 offset:3072
	ds_read_b128 v[196:199], v146 offset:4096
	ds_read_b128 v[200:203], v146 offset:5120
	ds_read_b128 v[210:213], v146 offset:6144
	ds_read_b128 v[214:217], v146 offset:7168
	s_waitcnt vmcnt(8)
	s_waitcnt lgkmcnt(0)
	s_barrier
	s_setprio 1
	s_waitcnt lgkmcnt(0)
	v_mfma_f32_16x16x32_bf16 v[128:131], v[148:151], v[180:183], v[128:131]
	v_mfma_f32_16x16x32_bf16 v[124:127], v[156:159], v[180:183], v[124:127]
	v_mfma_f32_16x16x32_bf16 v[112:115], v[148:151], v[188:191], v[112:115]
	v_mfma_f32_16x16x32_bf16 v[108:111], v[156:159], v[188:191], v[108:111]
	v_mfma_f32_16x16x32_bf16 v[96:99], v[148:151], v[196:199], v[96:99]
	v_mfma_f32_16x16x32_bf16 v[92:95], v[156:159], v[196:199], v[92:95]
	v_mfma_f32_16x16x32_bf16 v[80:83], v[148:151], v[210:213], v[80:83]
	v_mfma_f32_16x16x32_bf16 v[76:79], v[156:159], v[210:213], v[76:79]
	v_mfma_f32_16x16x32_bf16 v[128:131], v[152:155], v[184:187], v[128:131]
	v_mfma_f32_16x16x32_bf16 v[124:127], v[160:163], v[184:187], v[124:127]
	v_mfma_f32_16x16x32_bf16 v[112:115], v[152:155], v[192:195], v[112:115]
	v_mfma_f32_16x16x32_bf16 v[108:111], v[160:163], v[192:195], v[108:111]
	v_mfma_f32_16x16x32_bf16 v[96:99], v[152:155], v[200:203], v[96:99]
	v_mfma_f32_16x16x32_bf16 v[92:95], v[160:163], v[200:203], v[92:95]
	v_mfma_f32_16x16x32_bf16 v[80:83], v[152:155], v[214:217], v[80:83]
	v_mfma_f32_16x16x32_bf16 v[76:79], v[160:163], v[214:217], v[76:79]
	s_setprio 0
	s_setprio 1
	v_mfma_f32_16x16x32_bf16 v[120:123], v[164:167], v[180:183], v[120:123]
	v_mfma_f32_16x16x32_bf16 v[116:119], v[172:175], v[180:183], v[116:119]
	v_mfma_f32_16x16x32_bf16 v[104:107], v[164:167], v[188:191], v[104:107]
	v_mfma_f32_16x16x32_bf16 v[100:103], v[172:175], v[188:191], v[100:103]
	v_mfma_f32_16x16x32_bf16 v[88:91], v[164:167], v[196:199], v[88:91]
	v_mfma_f32_16x16x32_bf16 v[84:87], v[172:175], v[196:199], v[84:87]
	v_mfma_f32_16x16x32_bf16 v[72:75], v[164:167], v[210:213], v[72:75]
	v_mfma_f32_16x16x32_bf16 v[68:71], v[172:175], v[210:213], v[68:71]
	v_mfma_f32_16x16x32_bf16 v[120:123], v[168:171], v[184:187], v[120:123]
	v_mfma_f32_16x16x32_bf16 v[116:119], v[176:179], v[184:187], v[116:119]
	v_mfma_f32_16x16x32_bf16 v[104:107], v[168:171], v[192:195], v[104:107]
	v_mfma_f32_16x16x32_bf16 v[100:103], v[176:179], v[192:195], v[100:103]
	v_mfma_f32_16x16x32_bf16 v[88:91], v[168:171], v[200:203], v[88:91]
	v_mfma_f32_16x16x32_bf16 v[84:87], v[176:179], v[200:203], v[84:87]
	v_mfma_f32_16x16x32_bf16 v[72:75], v[168:171], v[214:217], v[72:75]
	v_mfma_f32_16x16x32_bf16 v[68:71], v[176:179], v[214:217], v[68:71]
	s_setprio 0
	s_barrier
	s_add_i32 s57, s33, s35
	s_mov_b32 m0, s57
	s_nop 0
	global_load_lds_dwordx4 v2, s[90:91]
	s_add_i32 m0, s57, 0x2000
	s_add_u32 s76, s90, 0x80000
	s_addc_u32 s77, s91, 0
	s_add_i32 s57, s96, s35
	global_load_lds_dwordx4 v132, s[90:91]
	s_mov_b32 m0, s57
	s_nop 0
	global_load_lds_dwordx4 v2, s[76:77]
	s_add_i32 m0, s57, 0x2000
	s_nop 0
	global_load_lds_dwordx4 v132, s[76:77]
	s_mov_b32 m0, s60
	s_nop 0
	global_load_lds_dwordx4 v136, vcc
	s_mov_b32 m0, s61
	s_nop 0
	global_load_lds_dwordx4 v134, vcc
	ds_read_b128 v[180:183], v146 offset:16384
	ds_read_b128 v[184:187], v146 offset:17408
	ds_read_b128 v[188:191], v146 offset:18432
	ds_read_b128 v[192:195], v146 offset:19456
	ds_read_b128 v[196:199], v146 offset:20480
	ds_read_b128 v[200:203], v146 offset:21504
	ds_read_b128 v[210:213], v146 offset:22528
	ds_read_b128 v[214:217], v146 offset:23552
	s_waitcnt vmcnt(8)
	s_waitcnt lgkmcnt(0)
	s_barrier
	s_setprio 1
	s_waitcnt lgkmcnt(0)
	v_mfma_f32_16x16x32_bf16 v[64:67], v[148:151], v[180:183], v[64:67]
	v_mfma_f32_16x16x32_bf16 v[60:63], v[156:159], v[180:183], v[60:63]
	v_mfma_f32_16x16x32_bf16 v[48:51], v[148:151], v[188:191], v[48:51]
	v_mfma_f32_16x16x32_bf16 v[44:47], v[156:159], v[188:191], v[44:47]
	v_mfma_f32_16x16x32_bf16 v[32:35], v[148:151], v[196:199], v[32:35]
	v_mfma_f32_16x16x32_bf16 v[28:31], v[156:159], v[196:199], v[28:31]
	v_mfma_f32_16x16x32_bf16 v[16:19], v[148:151], v[210:213], v[16:19]
	v_mfma_f32_16x16x32_bf16 v[12:15], v[156:159], v[210:213], v[12:15]
	v_mfma_f32_16x16x32_bf16 v[64:67], v[152:155], v[184:187], v[64:67]
	v_mfma_f32_16x16x32_bf16 v[60:63], v[160:163], v[184:187], v[60:63]
	v_mfma_f32_16x16x32_bf16 v[48:51], v[152:155], v[192:195], v[48:51]
	v_mfma_f32_16x16x32_bf16 v[44:47], v[160:163], v[192:195], v[44:47]
	v_mfma_f32_16x16x32_bf16 v[32:35], v[152:155], v[200:203], v[32:35]
	v_mfma_f32_16x16x32_bf16 v[28:31], v[160:163], v[200:203], v[28:31]
	v_mfma_f32_16x16x32_bf16 v[16:19], v[152:155], v[214:217], v[16:19]
	v_mfma_f32_16x16x32_bf16 v[12:15], v[160:163], v[214:217], v[12:15]
	s_setprio 0
	s_setprio 1
	v_mfma_f32_16x16x32_bf16 v[56:59], v[164:167], v[180:183], v[56:59]
	v_mfma_f32_16x16x32_bf16 v[52:55], v[172:175], v[180:183], v[52:55]
	v_mfma_f32_16x16x32_bf16 v[40:43], v[164:167], v[188:191], v[40:43]
	v_mfma_f32_16x16x32_bf16 v[36:39], v[172:175], v[188:191], v[36:39]
	v_mfma_f32_16x16x32_bf16 v[24:27], v[164:167], v[196:199], v[24:27]
	v_mfma_f32_16x16x32_bf16 v[20:23], v[172:175], v[196:199], v[20:23]
	v_mfma_f32_16x16x32_bf16 v[8:11], v[164:167], v[210:213], v[8:11]
	v_mfma_f32_16x16x32_bf16 v[4:7], v[172:175], v[210:213], v[4:7]
	v_mfma_f32_16x16x32_bf16 v[56:59], v[168:171], v[184:187], v[56:59]
	v_mfma_f32_16x16x32_bf16 v[52:55], v[176:179], v[184:187], v[52:55]
	v_mfma_f32_16x16x32_bf16 v[40:43], v[168:171], v[192:195], v[40:43]
	v_mfma_f32_16x16x32_bf16 v[36:39], v[176:179], v[192:195], v[36:39]
	v_mfma_f32_16x16x32_bf16 v[24:27], v[168:171], v[200:203], v[24:27]
	v_mfma_f32_16x16x32_bf16 v[20:23], v[176:179], v[200:203], v[20:23]
	v_mfma_f32_16x16x32_bf16 v[8:11], v[168:171], v[214:217], v[8:11]
	v_mfma_f32_16x16x32_bf16 v[4:7], v[176:179], v[214:217], v[4:7]
	s_setprio 0
	s_barrier
	s_add_u32 s76, vcc_lo, 0x80000
	s_addc_u32 s77, vcc_hi, 0
	s_mov_b32 m0, s62
	s_nop 0
	global_load_lds_dwordx4 v136, s[76:77]
	s_mov_b32 m0, s63
	s_nop 0
	global_load_lds_dwordx4 v134, s[76:77]
	ds_read_b128 v[148:151], v248
	ds_read_b128 v[152:155], v248 offset:1024
	ds_read_b128 v[156:159], v248 offset:2048
	ds_read_b128 v[160:163], v248 offset:3072
	ds_read_b128 v[164:167], v249
	ds_read_b128 v[168:171], v249 offset:1024
	ds_read_b128 v[172:175], v249 offset:2048
	ds_read_b128 v[176:179], v249 offset:3072
	ds_read_b128 v[180:183], v146 offset:32768
	ds_read_b128 v[184:187], v146 offset:33792
	ds_read_b128 v[188:191], v146 offset:34816
	ds_read_b128 v[192:195], v146 offset:35840
	ds_read_b128 v[196:199], v146 offset:36864
	ds_read_b128 v[200:203], v146 offset:37888
	ds_read_b128 v[210:213], v146 offset:38912
	ds_read_b128 v[214:217], v146 offset:39936
	s_waitcnt vmcnt(8)
	s_waitcnt lgkmcnt(0)
	s_barrier
	s_setprio 1
	s_waitcnt lgkmcnt(0)
	v_mfma_f32_16x16x32_bf16 v[128:131], v[148:151], v[180:183], v[128:131]
	v_mfma_f32_16x16x32_bf16 v[124:127], v[156:159], v[180:183], v[124:127]
	v_mfma_f32_16x16x32_bf16 v[112:115], v[148:151], v[188:191], v[112:115]
	v_mfma_f32_16x16x32_bf16 v[108:111], v[156:159], v[188:191], v[108:111]
	v_mfma_f32_16x16x32_bf16 v[96:99], v[148:151], v[196:199], v[96:99]
	v_mfma_f32_16x16x32_bf16 v[92:95], v[156:159], v[196:199], v[92:95]
	v_mfma_f32_16x16x32_bf16 v[80:83], v[148:151], v[210:213], v[80:83]
	v_mfma_f32_16x16x32_bf16 v[76:79], v[156:159], v[210:213], v[76:79]
	v_mfma_f32_16x16x32_bf16 v[128:131], v[152:155], v[184:187], v[128:131]
	v_mfma_f32_16x16x32_bf16 v[124:127], v[160:163], v[184:187], v[124:127]
	v_mfma_f32_16x16x32_bf16 v[112:115], v[152:155], v[192:195], v[112:115]
	v_mfma_f32_16x16x32_bf16 v[108:111], v[160:163], v[192:195], v[108:111]
	v_mfma_f32_16x16x32_bf16 v[96:99], v[152:155], v[200:203], v[96:99]
	v_mfma_f32_16x16x32_bf16 v[92:95], v[160:163], v[200:203], v[92:95]
	v_mfma_f32_16x16x32_bf16 v[80:83], v[152:155], v[214:217], v[80:83]
	v_mfma_f32_16x16x32_bf16 v[76:79], v[160:163], v[214:217], v[76:79]
	s_setprio 0
	s_setprio 1
	v_mfma_f32_16x16x32_bf16 v[120:123], v[164:167], v[180:183], v[120:123]
	v_mfma_f32_16x16x32_bf16 v[116:119], v[172:175], v[180:183], v[116:119]
	v_mfma_f32_16x16x32_bf16 v[104:107], v[164:167], v[188:191], v[104:107]
	v_mfma_f32_16x16x32_bf16 v[100:103], v[172:175], v[188:191], v[100:103]
	v_mfma_f32_16x16x32_bf16 v[88:91], v[164:167], v[196:199], v[88:91]
	v_mfma_f32_16x16x32_bf16 v[84:87], v[172:175], v[196:199], v[84:87]
	v_mfma_f32_16x16x32_bf16 v[72:75], v[164:167], v[210:213], v[72:75]
	v_mfma_f32_16x16x32_bf16 v[68:71], v[172:175], v[210:213], v[68:71]
	v_mfma_f32_16x16x32_bf16 v[120:123], v[168:171], v[184:187], v[120:123]
	v_mfma_f32_16x16x32_bf16 v[116:119], v[176:179], v[184:187], v[116:119]
	v_mfma_f32_16x16x32_bf16 v[104:107], v[168:171], v[192:195], v[104:107]
	v_mfma_f32_16x16x32_bf16 v[100:103], v[176:179], v[192:195], v[100:103]
	v_mfma_f32_16x16x32_bf16 v[88:91], v[168:171], v[200:203], v[88:91]
	v_mfma_f32_16x16x32_bf16 v[84:87], v[176:179], v[200:203], v[84:87]
	v_mfma_f32_16x16x32_bf16 v[72:75], v[168:171], v[214:217], v[72:75]
	v_mfma_f32_16x16x32_bf16 v[68:71], v[176:179], v[214:217], v[68:71]
	s_setprio 0
	s_barrier
	s_add_i32 s57, s97, s35
	s_mov_b32 m0, s57
	s_nop 0
	s_add_u32 s98, s90, 0x80
	s_addc_u32 s99, s91, 0
	s_nop 0
	global_load_lds_dwordx4 v2, s[98:99]
	s_add_i32 m0, s57, 0x2000
	s_add_u32 s76, s90, 0x80080
	s_addc_u32 s77, s91, 0
	s_add_i32 s57, s48, s35
	global_load_lds_dwordx4 v132, s[98:99]
	s_mov_b32 m0, s57
	s_nop 0
	global_load_lds_dwordx4 v2, s[76:77]
	s_add_i32 m0, s57, 0x2000
	s_nop 0
	global_load_lds_dwordx4 v132, s[76:77]
	s_mov_b32 m0, s64
	s_nop 0
	s_add_u32 s98, vcc_lo, 0x80
	s_addc_u32 s99, vcc_hi, 0
	s_nop 0
	global_load_lds_dwordx4 v136, s[98:99]
	s_mov_b32 m0, s58
	s_nop 0
	global_load_lds_dwordx4 v134, s[98:99]
	ds_read_b128 v[180:183], v146 offset:49152
	ds_read_b128 v[184:187], v146 offset:50176
	ds_read_b128 v[188:191], v146 offset:51200
	ds_read_b128 v[192:195], v146 offset:52224
	ds_read_b128 v[196:199], v146 offset:53248
	ds_read_b128 v[200:203], v146 offset:54272
	ds_read_b128 v[210:213], v146 offset:55296
	ds_read_b128 v[214:217], v146 offset:56320
	s_waitcnt vmcnt(8)
	s_waitcnt lgkmcnt(0)
	s_barrier
	s_setprio 1
	s_waitcnt lgkmcnt(0)
	v_mfma_f32_16x16x32_bf16 v[64:67], v[148:151], v[180:183], v[64:67]
	v_mfma_f32_16x16x32_bf16 v[60:63], v[156:159], v[180:183], v[60:63]
	v_mfma_f32_16x16x32_bf16 v[48:51], v[148:151], v[188:191], v[48:51]
	v_mfma_f32_16x16x32_bf16 v[44:47], v[156:159], v[188:191], v[44:47]
	v_mfma_f32_16x16x32_bf16 v[32:35], v[148:151], v[196:199], v[32:35]
	v_mfma_f32_16x16x32_bf16 v[28:31], v[156:159], v[196:199], v[28:31]
	v_mfma_f32_16x16x32_bf16 v[16:19], v[148:151], v[210:213], v[16:19]
	v_mfma_f32_16x16x32_bf16 v[12:15], v[156:159], v[210:213], v[12:15]
	v_mfma_f32_16x16x32_bf16 v[64:67], v[152:155], v[184:187], v[64:67]
	v_mfma_f32_16x16x32_bf16 v[60:63], v[160:163], v[184:187], v[60:63]
	v_mfma_f32_16x16x32_bf16 v[48:51], v[152:155], v[192:195], v[48:51]
	v_mfma_f32_16x16x32_bf16 v[44:47], v[160:163], v[192:195], v[44:47]
	v_mfma_f32_16x16x32_bf16 v[32:35], v[152:155], v[200:203], v[32:35]
	v_mfma_f32_16x16x32_bf16 v[28:31], v[160:163], v[200:203], v[28:31]
	v_mfma_f32_16x16x32_bf16 v[16:19], v[152:155], v[214:217], v[16:19]
	v_mfma_f32_16x16x32_bf16 v[12:15], v[160:163], v[214:217], v[12:15]
	s_setprio 0
	s_setprio 1
	v_mfma_f32_16x16x32_bf16 v[56:59], v[164:167], v[180:183], v[56:59]
	v_mfma_f32_16x16x32_bf16 v[52:55], v[172:175], v[180:183], v[52:55]
	v_mfma_f32_16x16x32_bf16 v[40:43], v[164:167], v[188:191], v[40:43]
	v_mfma_f32_16x16x32_bf16 v[36:39], v[172:175], v[188:191], v[36:39]
	v_mfma_f32_16x16x32_bf16 v[24:27], v[164:167], v[196:199], v[24:27]
	v_mfma_f32_16x16x32_bf16 v[20:23], v[172:175], v[196:199], v[20:23]
	v_mfma_f32_16x16x32_bf16 v[8:11], v[164:167], v[210:213], v[8:11]
	v_mfma_f32_16x16x32_bf16 v[4:7], v[172:175], v[210:213], v[4:7]
	v_mfma_f32_16x16x32_bf16 v[56:59], v[168:171], v[184:187], v[56:59]
	v_mfma_f32_16x16x32_bf16 v[52:55], v[176:179], v[184:187], v[52:55]
	v_mfma_f32_16x16x32_bf16 v[40:43], v[168:171], v[192:195], v[40:43]
	v_mfma_f32_16x16x32_bf16 v[36:39], v[176:179], v[192:195], v[36:39]
	v_mfma_f32_16x16x32_bf16 v[24:27], v[168:171], v[200:203], v[24:27]
	v_mfma_f32_16x16x32_bf16 v[20:23], v[176:179], v[200:203], v[20:23]
	v_mfma_f32_16x16x32_bf16 v[8:11], v[168:171], v[214:217], v[8:11]
	v_mfma_f32_16x16x32_bf16 v[4:7], v[176:179], v[214:217], v[4:7]
	s_setprio 0
	s_barrier
	s_add_i32 s56, s56, 2
	s_add_u32 s88, s88, 0x100
	s_addc_u32 s89, s89, 0
	s_add_u32 s54, s54, 0x100
	s_addc_u32 s55, s55, 0
	s_cmp_gt_u32 s56, 29
	s_cbranch_scc0 .LBB0_694
	s_and_b64 vcc, exec, s[68:69]
	s_cbranch_vccz .LBB0_697
	s_barrier

.LBB0_762:
	s_add_i32 s23, s51, -2
	s_add_u32 s84, s84, 0x200080
	s_addc_u32 s85, s85, 0
	s_add_u32 s29, s86, 0x100
	s_addc_u32 s35, s87, 0
	s_mov_b32 s55, 0
	v_mov_b64_e32 v[4:5], 0
	v_mov_b64_e32 v[6:7], 0
	v_mov_b64_e32 v[8:9], 0
	v_mov_b64_e32 v[10:11], 0
	v_mov_b64_e32 v[12:13], 0
	v_mov_b64_e32 v[14:15], 0
	v_mov_b64_e32 v[16:17], 0
	v_mov_b64_e32 v[18:19], 0
	v_mov_b64_e32 v[20:21], 0
	v_mov_b64_e32 v[22:23], 0
	v_mov_b64_e32 v[24:25], 0
	v_mov_b64_e32 v[26:27], 0
	v_mov_b64_e32 v[28:29], 0
	v_mov_b64_e32 v[30:31], 0
	v_mov_b64_e32 v[32:33], 0
	v_mov_b64_e32 v[34:35], 0
	v_mov_b64_e32 v[36:37], 0
	v_mov_b64_e32 v[38:39], 0
	v_mov_b64_e32 v[40:41], 0
	v_mov_b64_e32 v[42:43], 0
	v_mov_b64_e32 v[44:45], 0
	v_mov_b64_e32 v[46:47], 0
	v_mov_b64_e32 v[48:49], 0
	v_mov_b64_e32 v[50:51], 0
	v_mov_b64_e32 v[52:53], 0
	v_mov_b64_e32 v[54:55], 0
	v_mov_b64_e32 v[56:57], 0
	v_mov_b64_e32 v[58:59], 0
	v_mov_b64_e32 v[60:61], 0
	v_mov_b64_e32 v[62:63], 0
	v_mov_b64_e32 v[64:65], 0
	v_mov_b64_e32 v[66:67], 0
	v_mov_b64_e32 v[68:69], 0
	v_mov_b64_e32 v[70:71], 0
	v_mov_b64_e32 v[72:73], 0
	v_mov_b64_e32 v[74:75], 0
	v_mov_b64_e32 v[76:77], 0
	v_mov_b64_e32 v[78:79], 0
	v_mov_b64_e32 v[80:81], 0
	v_mov_b64_e32 v[82:83], 0
	v_mov_b64_e32 v[84:85], 0
	v_mov_b64_e32 v[86:87], 0
	v_mov_b64_e32 v[88:89], 0
	v_mov_b64_e32 v[90:91], 0
	v_mov_b64_e32 v[92:93], 0
	v_mov_b64_e32 v[94:95], 0
	v_mov_b64_e32 v[96:97], 0
	v_mov_b64_e32 v[98:99], 0
	v_mov_b64_e32 v[100:101], 0
	v_mov_b64_e32 v[102:103], 0
	v_mov_b64_e32 v[104:105], 0
	v_mov_b64_e32 v[106:107], 0
	v_mov_b64_e32 v[108:109], 0
	v_mov_b64_e32 v[110:111], 0
	v_mov_b64_e32 v[112:113], 0
	v_mov_b64_e32 v[114:115], 0
	v_mov_b64_e32 v[116:117], 0
	v_mov_b64_e32 v[118:119], 0
	v_mov_b64_e32 v[120:121], 0
	v_mov_b64_e32 v[122:123], 0
	v_mov_b64_e32 v[124:125], 0
	v_mov_b64_e32 v[126:127], 0
	v_mov_b64_e32 v[128:129], 0
	v_mov_b64_e32 v[130:131], 0
	v_add_u32_e32 v246, 0x10000, v142
	v_add_u32_e32 v247, 0x14000, v142
	v_add_u32_e32 v248, 0x18000, v142
	v_add_u32_e32 v249, 0x1c000, v142
.LBB0_763:
	s_add_i32 s56, s55, 2
	s_add_u32 s57, s84, 0xffe00080
	s_addc_u32 s62, s85, -1
	s_add_i32 m0, s16, 0xc000
	s_add_i32 s63, s16, 0xe000
	global_load_lds_dwordx4 v138, s[84:85]
	s_mov_b32 m0, s63
	s_cmp_eq_u32 s23, s55
	global_load_lds_dwordx4 v140, s[84:85]
	s_cselect_b32 s89, s73, s62
	s_cselect_b32 s88, s72, s57
	s_cselect_b32 s87, s75, s35
	s_cselect_b32 s86, s74, s29
	ds_read_b128 v[146:149], v246
	ds_read_b128 v[150:153], v246 offset:1024
	ds_read_b128 v[154:157], v246 offset:2048
	ds_read_b128 v[158:161], v246 offset:3072
	ds_read_b128 v[162:165], v247
	ds_read_b128 v[166:169], v247 offset:1024
	ds_read_b128 v[170:173], v247 offset:2048
	ds_read_b128 v[174:177], v247 offset:3072
	ds_read_b128 v[178:181], v144
	ds_read_b128 v[182:185], v144 offset:1024
	ds_read_b128 v[186:189], v144 offset:2048
	ds_read_b128 v[190:193], v144 offset:3072
	ds_read_b128 v[194:197], v144 offset:4096
	ds_read_b128 v[198:201], v144 offset:5120
	ds_read_b128 v[202:205], v144 offset:6144
	ds_read_b128 v[210:213], v144 offset:7168
	s_waitcnt vmcnt(8)
	s_waitcnt lgkmcnt(0)
	s_barrier
	s_setprio 1
	s_waitcnt lgkmcnt(0)
	v_mfma_f32_16x16x32_bf16 v[128:131], v[146:149], v[178:181], v[128:131]
	v_mfma_f32_16x16x32_bf16 v[124:127], v[154:157], v[178:181], v[124:127]
	v_mfma_f32_16x16x32_bf16 v[120:123], v[146:149], v[186:189], v[120:123]
	v_mfma_f32_16x16x32_bf16 v[116:119], v[154:157], v[186:189], v[116:119]
	v_mfma_f32_16x16x32_bf16 v[104:107], v[146:149], v[194:197], v[104:107]
	v_mfma_f32_16x16x32_bf16 v[100:103], v[154:157], v[194:197], v[100:103]
	v_mfma_f32_16x16x32_bf16 v[88:91], v[146:149], v[202:205], v[88:91]
	v_mfma_f32_16x16x32_bf16 v[84:87], v[154:157], v[202:205], v[84:87]
	v_mfma_f32_16x16x32_bf16 v[128:131], v[150:153], v[182:185], v[128:131]
	v_mfma_f32_16x16x32_bf16 v[124:127], v[158:161], v[182:185], v[124:127]
	v_mfma_f32_16x16x32_bf16 v[120:123], v[150:153], v[190:193], v[120:123]
	v_mfma_f32_16x16x32_bf16 v[116:119], v[158:161], v[190:193], v[116:119]
	v_mfma_f32_16x16x32_bf16 v[104:107], v[150:153], v[198:201], v[104:107]
	v_mfma_f32_16x16x32_bf16 v[100:103], v[158:161], v[198:201], v[100:103]
	v_mfma_f32_16x16x32_bf16 v[88:91], v[150:153], v[210:213], v[88:91]
	v_mfma_f32_16x16x32_bf16 v[84:87], v[158:161], v[210:213], v[84:87]
	s_setprio 0
	s_setprio 1
	v_mfma_f32_16x16x32_bf16 v[112:115], v[162:165], v[178:181], v[112:115]
	v_mfma_f32_16x16x32_bf16 v[108:111], v[170:173], v[178:181], v[108:111]
	v_mfma_f32_16x16x32_bf16 v[96:99], v[162:165], v[186:189], v[96:99]
	v_mfma_f32_16x16x32_bf16 v[92:95], v[170:173], v[186:189], v[92:95]
	v_mfma_f32_16x16x32_bf16 v[80:83], v[162:165], v[194:197], v[80:83]
	v_mfma_f32_16x16x32_bf16 v[76:79], v[170:173], v[194:197], v[76:79]
	v_mfma_f32_16x16x32_bf16 v[72:75], v[162:165], v[202:205], v[72:75]
	v_mfma_f32_16x16x32_bf16 v[68:71], v[170:173], v[202:205], v[68:71]
	v_mfma_f32_16x16x32_bf16 v[112:115], v[166:169], v[182:185], v[112:115]
	v_mfma_f32_16x16x32_bf16 v[108:111], v[174:177], v[182:185], v[108:111]
	v_mfma_f32_16x16x32_bf16 v[96:99], v[166:169], v[190:193], v[96:99]
	v_mfma_f32_16x16x32_bf16 v[92:95], v[174:177], v[190:193], v[92:95]
	v_mfma_f32_16x16x32_bf16 v[80:83], v[166:169], v[198:201], v[80:83]
	v_mfma_f32_16x16x32_bf16 v[76:79], v[174:177], v[198:201], v[76:79]
	v_mfma_f32_16x16x32_bf16 v[72:75], v[166:169], v[210:213], v[72:75]
	v_mfma_f32_16x16x32_bf16 v[68:71], v[174:177], v[210:213], v[68:71]
	s_setprio 0
	s_barrier
	s_add_i32 s55, s33, s13
	s_mov_b32 m0, s55
	s_nop 0
	global_load_lds_dwordx4 v2, s[86:87]
	s_add_i32 m0, s55, 0x2000
	s_add_u32 s62, s86, 0x200000
	s_addc_u32 s63, s87, 0
	s_add_i32 s55, s96, s13
	global_load_lds_dwordx4 v136, s[86:87]
	s_mov_b32 m0, s55
	s_nop 0
	global_load_lds_dwordx4 v2, s[62:63]
	s_add_i32 m0, s55, 0x2000
	s_nop 0
	global_load_lds_dwordx4 v136, s[62:63]
	s_mov_b32 m0, s16
	s_nop 0
	global_load_lds_dwordx4 v132, s[88:89]
	s_mov_b32 m0, s17
	s_nop 0
	global_load_lds_dwordx4 v134, s[88:89]
	ds_read_b128 v[178:181], v144 offset:16384
	ds_read_b128 v[182:185], v144 offset:17408
	ds_read_b128 v[186:189], v144 offset:18432
	ds_read_b128 v[190:193], v144 offset:19456
	ds_read_b128 v[194:197], v144 offset:20480
	ds_read_b128 v[198:201], v144 offset:21504
	ds_read_b128 v[202:205], v144 offset:22528
	ds_read_b128 v[210:213], v144 offset:23552
	s_waitcnt vmcnt(8)
	s_waitcnt lgkmcnt(0)
	s_barrier
	s_setprio 1
	s_waitcnt lgkmcnt(0)
	v_mfma_f32_16x16x32_bf16 v[64:67], v[146:149], v[178:181], v[64:67]
	v_mfma_f32_16x16x32_bf16 v[60:63], v[154:157], v[178:181], v[60:63]
	v_mfma_f32_16x16x32_bf16 v[56:59], v[146:149], v[186:189], v[56:59]
	v_mfma_f32_16x16x32_bf16 v[52:55], v[154:157], v[186:189], v[52:55]
	v_mfma_f32_16x16x32_bf16 v[40:43], v[146:149], v[194:197], v[40:43]
	v_mfma_f32_16x16x32_bf16 v[36:39], v[154:157], v[194:197], v[36:39]
	v_mfma_f32_16x16x32_bf16 v[24:27], v[146:149], v[202:205], v[24:27]
	v_mfma_f32_16x16x32_bf16 v[20:23], v[154:157], v[202:205], v[20:23]
	v_mfma_f32_16x16x32_bf16 v[64:67], v[150:153], v[182:185], v[64:67]
	v_mfma_f32_16x16x32_bf16 v[60:63], v[158:161], v[182:185], v[60:63]
	v_mfma_f32_16x16x32_bf16 v[56:59], v[150:153], v[190:193], v[56:59]
	v_mfma_f32_16x16x32_bf16 v[52:55], v[158:161], v[190:193], v[52:55]
	v_mfma_f32_16x16x32_bf16 v[40:43], v[150:153], v[198:201], v[40:43]
	v_mfma_f32_16x16x32_bf16 v[36:39], v[158:161], v[198:201], v[36:39]
	v_mfma_f32_16x16x32_bf16 v[24:27], v[150:153], v[210:213], v[24:27]
	v_mfma_f32_16x16x32_bf16 v[20:23], v[158:161], v[210:213], v[20:23]
	s_setprio 0
	s_setprio 1
	v_mfma_f32_16x16x32_bf16 v[48:51], v[162:165], v[178:181], v[48:51]
	v_mfma_f32_16x16x32_bf16 v[44:47], v[170:173], v[178:181], v[44:47]
	v_mfma_f32_16x16x32_bf16 v[32:35], v[162:165], v[186:189], v[32:35]
	v_mfma_f32_16x16x32_bf16 v[28:31], v[170:173], v[186:189], v[28:31]
	v_mfma_f32_16x16x32_bf16 v[16:19], v[162:165], v[194:197], v[16:19]
	v_mfma_f32_16x16x32_bf16 v[12:15], v[170:173], v[194:197], v[12:15]
	v_mfma_f32_16x16x32_bf16 v[8:11], v[162:165], v[202:205], v[8:11]
	v_mfma_f32_16x16x32_bf16 v[4:7], v[170:173], v[202:205], v[4:7]
	v_mfma_f32_16x16x32_bf16 v[48:51], v[166:169], v[182:185], v[48:51]
	v_mfma_f32_16x16x32_bf16 v[44:47], v[174:177], v[182:185], v[44:47]
	v_mfma_f32_16x16x32_bf16 v[32:35], v[166:169], v[190:193], v[32:35]
	v_mfma_f32_16x16x32_bf16 v[28:31], v[174:177], v[190:193], v[28:31]
	v_mfma_f32_16x16x32_bf16 v[16:19], v[166:169], v[198:201], v[16:19]
	v_mfma_f32_16x16x32_bf16 v[12:15], v[174:177], v[198:201], v[12:15]
	v_mfma_f32_16x16x32_bf16 v[8:11], v[166:169], v[210:213], v[8:11]
	v_mfma_f32_16x16x32_bf16 v[4:7], v[174:177], v[210:213], v[4:7]
	s_setprio 0
	s_barrier
	s_add_u32 s62, s88, 0x200000
	s_addc_u32 s63, s89, 0
	s_mov_b32 m0, s58
	s_nop 0
	global_load_lds_dwordx4 v132, s[62:63]
	s_mov_b32 m0, s59
	s_nop 0
	global_load_lds_dwordx4 v134, s[62:63]
	ds_read_b128 v[146:149], v248
	ds_read_b128 v[150:153], v248 offset:1024
	ds_read_b128 v[154:157], v248 offset:2048
	ds_read_b128 v[158:161], v248 offset:3072
	ds_read_b128 v[162:165], v249
	ds_read_b128 v[166:169], v249 offset:1024
	ds_read_b128 v[170:173], v249 offset:2048
	ds_read_b128 v[174:177], v249 offset:3072
	ds_read_b128 v[178:181], v144 offset:32768
	ds_read_b128 v[182:185], v144 offset:33792
	ds_read_b128 v[186:189], v144 offset:34816
	ds_read_b128 v[190:193], v144 offset:35840
	ds_read_b128 v[194:197], v144 offset:36864
	ds_read_b128 v[198:201], v144 offset:37888
	ds_read_b128 v[202:205], v144 offset:38912
	ds_read_b128 v[210:213], v144 offset:39936
	s_waitcnt vmcnt(8)
	s_waitcnt lgkmcnt(0)
	s_barrier
	s_setprio 1
	s_waitcnt lgkmcnt(0)
	v_mfma_f32_16x16x32_bf16 v[128:131], v[146:149], v[178:181], v[128:131]
	v_mfma_f32_16x16x32_bf16 v[124:127], v[154:157], v[178:181], v[124:127]
	v_mfma_f32_16x16x32_bf16 v[120:123], v[146:149], v[186:189], v[120:123]
	v_mfma_f32_16x16x32_bf16 v[116:119], v[154:157], v[186:189], v[116:119]
	v_mfma_f32_16x16x32_bf16 v[104:107], v[146:149], v[194:197], v[104:107]
	v_mfma_f32_16x16x32_bf16 v[100:103], v[154:157], v[194:197], v[100:103]
	v_mfma_f32_16x16x32_bf16 v[88:91], v[146:149], v[202:205], v[88:91]
	v_mfma_f32_16x16x32_bf16 v[84:87], v[154:157], v[202:205], v[84:87]
	v_mfma_f32_16x16x32_bf16 v[128:131], v[150:153], v[182:185], v[128:131]
	v_mfma_f32_16x16x32_bf16 v[124:127], v[158:161], v[182:185], v[124:127]
	v_mfma_f32_16x16x32_bf16 v[120:123], v[150:153], v[190:193], v[120:123]
	v_mfma_f32_16x16x32_bf16 v[116:119], v[158:161], v[190:193], v[116:119]
	v_mfma_f32_16x16x32_bf16 v[104:107], v[150:153], v[198:201], v[104:107]
	v_mfma_f32_16x16x32_bf16 v[100:103], v[158:161], v[198:201], v[100:103]
	v_mfma_f32_16x16x32_bf16 v[88:91], v[150:153], v[210:213], v[88:91]
	v_mfma_f32_16x16x32_bf16 v[84:87], v[158:161], v[210:213], v[84:87]
	s_setprio 0
	s_setprio 1
	v_mfma_f32_16x16x32_bf16 v[112:115], v[162:165], v[178:181], v[112:115]
	v_mfma_f32_16x16x32_bf16 v[108:111], v[170:173], v[178:181], v[108:111]
	v_mfma_f32_16x16x32_bf16 v[96:99], v[162:165], v[186:189], v[96:99]
	v_mfma_f32_16x16x32_bf16 v[92:95], v[170:173], v[186:189], v[92:95]
	v_mfma_f32_16x16x32_bf16 v[80:83], v[162:165], v[194:197], v[80:83]
	v_mfma_f32_16x16x32_bf16 v[76:79], v[170:173], v[194:197], v[76:79]
	v_mfma_f32_16x16x32_bf16 v[72:75], v[162:165], v[202:205], v[72:75]
	v_mfma_f32_16x16x32_bf16 v[68:71], v[170:173], v[202:205], v[68:71]
	v_mfma_f32_16x16x32_bf16 v[112:115], v[166:169], v[182:185], v[112:115]
	v_mfma_f32_16x16x32_bf16 v[108:111], v[174:177], v[182:185], v[108:111]
	v_mfma_f32_16x16x32_bf16 v[96:99], v[166:169], v[190:193], v[96:99]
	v_mfma_f32_16x16x32_bf16 v[92:95], v[174:177], v[190:193], v[92:95]
	v_mfma_f32_16x16x32_bf16 v[80:83], v[166:169], v[198:201], v[80:83]
	v_mfma_f32_16x16x32_bf16 v[76:79], v[174:177], v[198:201], v[76:79]
	v_mfma_f32_16x16x32_bf16 v[72:75], v[166:169], v[210:213], v[72:75]
	v_mfma_f32_16x16x32_bf16 v[68:71], v[174:177], v[210:213], v[68:71]
	s_setprio 0
	s_barrier
	s_add_i32 s55, s97, s13
	s_mov_b32 m0, s55
	s_nop 0
	s_add_u32 s98, s86, 0x80
	s_addc_u32 s99, s87, 0
	s_nop 0
	global_load_lds_dwordx4 v2, s[98:99]
	s_add_i32 m0, s55, 0x2000
	s_add_u32 s62, s86, 0x200080
	s_addc_u32 s63, s87, 0
	s_add_i32 s55, s48, s13
	global_load_lds_dwordx4 v136, s[98:99]
	s_mov_b32 m0, s55
	s_nop 0
	global_load_lds_dwordx4 v2, s[62:63]
	s_add_i32 m0, s55, 0x2000
	s_nop 0
	global_load_lds_dwordx4 v136, s[62:63]
	s_mov_b32 m0, s60
	s_nop 0
	s_add_u32 s98, s88, 0x80
	s_addc_u32 s99, s89, 0
	s_nop 0
	global_load_lds_dwordx4 v132, s[98:99]
	s_mov_b32 m0, s61
	s_nop 0
	global_load_lds_dwordx4 v134, s[98:99]
	ds_read_b128 v[178:181], v144 offset:49152
	ds_read_b128 v[182:185], v144 offset:50176
	ds_read_b128 v[186:189], v144 offset:51200
	ds_read_b128 v[190:193], v144 offset:52224
	ds_read_b128 v[194:197], v144 offset:53248
	ds_read_b128 v[198:201], v144 offset:54272
	ds_read_b128 v[202:205], v144 offset:55296
	ds_read_b128 v[210:213], v144 offset:56320
	s_waitcnt vmcnt(8)
	s_waitcnt lgkmcnt(0)
	s_barrier
	s_setprio 1
	s_waitcnt lgkmcnt(0)
	v_mfma_f32_16x16x32_bf16 v[64:67], v[146:149], v[178:181], v[64:67]
	v_mfma_f32_16x16x32_bf16 v[60:63], v[154:157], v[178:181], v[60:63]
	v_mfma_f32_16x16x32_bf16 v[56:59], v[146:149], v[186:189], v[56:59]
	v_mfma_f32_16x16x32_bf16 v[52:55], v[154:157], v[186:189], v[52:55]
	v_mfma_f32_16x16x32_bf16 v[40:43], v[146:149], v[194:197], v[40:43]
	v_mfma_f32_16x16x32_bf16 v[36:39], v[154:157], v[194:197], v[36:39]
	v_mfma_f32_16x16x32_bf16 v[24:27], v[146:149], v[202:205], v[24:27]
	v_mfma_f32_16x16x32_bf16 v[20:23], v[154:157], v[202:205], v[20:23]
	v_mfma_f32_16x16x32_bf16 v[64:67], v[150:153], v[182:185], v[64:67]
	v_mfma_f32_16x16x32_bf16 v[60:63], v[158:161], v[182:185], v[60:63]
	v_mfma_f32_16x16x32_bf16 v[56:59], v[150:153], v[190:193], v[56:59]
	v_mfma_f32_16x16x32_bf16 v[52:55], v[158:161], v[190:193], v[52:55]
	v_mfma_f32_16x16x32_bf16 v[40:43], v[150:153], v[198:201], v[40:43]
	v_mfma_f32_16x16x32_bf16 v[36:39], v[158:161], v[198:201], v[36:39]
	v_mfma_f32_16x16x32_bf16 v[24:27], v[150:153], v[210:213], v[24:27]
	v_mfma_f32_16x16x32_bf16 v[20:23], v[158:161], v[210:213], v[20:23]
	s_setprio 0
	s_setprio 1
	v_mfma_f32_16x16x32_bf16 v[48:51], v[162:165], v[178:181], v[48:51]
	v_mfma_f32_16x16x32_bf16 v[44:47], v[170:173], v[178:181], v[44:47]
	v_mfma_f32_16x16x32_bf16 v[32:35], v[162:165], v[186:189], v[32:35]
	v_mfma_f32_16x16x32_bf16 v[28:31], v[170:173], v[186:189], v[28:31]
	v_mfma_f32_16x16x32_bf16 v[16:19], v[162:165], v[194:197], v[16:19]
	v_mfma_f32_16x16x32_bf16 v[12:15], v[170:173], v[194:197], v[12:15]
	v_mfma_f32_16x16x32_bf16 v[8:11], v[162:165], v[202:205], v[8:11]
	v_mfma_f32_16x16x32_bf16 v[4:7], v[170:173], v[202:205], v[4:7]
	v_mfma_f32_16x16x32_bf16 v[48:51], v[166:169], v[182:185], v[48:51]
	v_mfma_f32_16x16x32_bf16 v[44:47], v[174:177], v[182:185], v[44:47]
	v_mfma_f32_16x16x32_bf16 v[32:35], v[166:169], v[190:193], v[32:35]
	v_mfma_f32_16x16x32_bf16 v[28:31], v[174:177], v[190:193], v[28:31]
	v_mfma_f32_16x16x32_bf16 v[16:19], v[166:169], v[198:201], v[16:19]
	v_mfma_f32_16x16x32_bf16 v[12:15], v[174:177], v[198:201], v[12:15]
	v_mfma_f32_16x16x32_bf16 v[8:11], v[166:169], v[210:213], v[8:11]
	v_mfma_f32_16x16x32_bf16 v[4:7], v[174:177], v[210:213], v[4:7]
	s_setprio 0
	s_barrier
	s_add_u32 s84, s84, 0x100
	s_addc_u32 s85, s85, 0
	s_add_u32 s29, s29, 0x100
	s_addc_u32 s35, s35, 0
	s_cmp_ge_u32 s56, s51
	s_mov_b32 s55, s56
	s_cbranch_scc0 .LBB0_763
	s_and_b64 vcc, exec, s[68:69]
	s_cbranch_vccz .LBB0_766
	s_barrier

	.amdhsa_kernel _Z10fwd_kernel4Args
		.amdhsa_group_segment_fixed_size 0
		.amdhsa_private_segment_fixed_size 0
		.amdhsa_kernarg_size 464
		.amdhsa_user_sgpr_count 2
		.amdhsa_user_sgpr_dispatch_ptr 0
		.amdhsa_user_sgpr_queue_ptr 0
		.amdhsa_user_sgpr_kernarg_segment_ptr 1
		.amdhsa_user_sgpr_dispatch_id 0
		.amdhsa_user_sgpr_kernarg_preload_length 0
		.amdhsa_user_sgpr_kernarg_preload_offset 0
		.amdhsa_user_sgpr_private_segment_size 0
		.amdhsa_uses_dynamic_stack 0
		.amdhsa_enable_private_segment 0
		.amdhsa_system_sgpr_workgroup_id_x 1
		.amdhsa_system_sgpr_workgroup_id_y 0
		.amdhsa_system_sgpr_workgroup_id_z 0
		.amdhsa_system_sgpr_workgroup_info 0
		.amdhsa_system_vgpr_workitem_id 0
		.amdhsa_next_free_vgpr 255
		.amdhsa_next_free_sgpr 100
		.amdhsa_accum_offset 256
		.amdhsa_reserve_vcc 1
		.amdhsa_float_round_mode_32 0
		.amdhsa_float_round_mode_16_64 0
		.amdhsa_float_denorm_mode_32 3
		.amdhsa_float_denorm_mode_16_64 3
		.amdhsa_dx10_clamp 1
		.amdhsa_ieee_mode 1
		.amdhsa_fp16_overflow 0
		.amdhsa_tg_split 0
		.amdhsa_exception_fp_ieee_invalid_op 0
		.amdhsa_exception_fp_denorm_src 0
		.amdhsa_exception_fp_ieee_div_zero 0
		.amdhsa_exception_fp_ieee_overflow 0
		.amdhsa_exception_fp_ieee_underflow 0
		.amdhsa_exception_fp_ieee_inexact 0
		.amdhsa_exception_int_div_zero 0
	.end_amdhsa_kernel

amdhsa.kernels:
  - .agpr_count:     0
    .args:
      - .offset:         0
        .size:           208
        .value_kind:     by_value
      - .offset:         208
        .size:           4
        .value_kind:     hidden_block_count_x
      - .offset:         212
        .size:           4
        .value_kind:     hidden_block_count_y
      - .offset:         216
        .size:           4
        .value_kind:     hidden_block_count_z
      - .offset:         220
        .size:           2
        .value_kind:     hidden_group_size_x
      - .offset:         222
        .size:           2
        .value_kind:     hidden_group_size_y
      - .offset:         224
        .size:           2
        .value_kind:     hidden_group_size_z
      - .offset:         226
        .size:           2
        .value_kind:     hidden_remainder_x
      - .offset:         228
        .size:           2
        .value_kind:     hidden_remainder_y
      - .offset:         230
        .size:           2
        .value_kind:     hidden_remainder_z
      - .offset:         248
        .size:           8
        .value_kind:     hidden_global_offset_x
      - .offset:         256
        .size:           8
        .value_kind:     hidden_global_offset_y
      - .offset:         264
        .size:           8
        .value_kind:     hidden_global_offset_z
      - .offset:         272
        .size:           2
        .value_kind:     hidden_grid_dims
      - .offset:         328
        .size:           4
        .value_kind:     hidden_dynamic_lds_size
    .group_segment_fixed_size: 0
    .kernarg_segment_align: 8
    .kernarg_segment_size: 464
    .language:       OpenCL C
    .language_version:
      - 2
      - 0
    .max_flat_workgroup_size: 512
    .name:           _Z10fwd_kernel4Args
    .private_segment_fixed_size: 0
    .sgpr_count:     106
    .sgpr_spill_count: 185
    .symbol:         _Z10fwd_kernel4Args.kd
    .uniform_work_group_size: 1
    .uses_dynamic_stack: false
    .vgpr_count:     255
    .vgpr_spill_count: 0
    .wavefront_size: 64
